# s10 + setprio_mid: the s_setprio 0/1 pair in the middle of each 32-MFMA block deleted (20 sites)
# speedup vs baseline: 1.0036x; 1.0036x over previous
.LBB0_124:
	ds_read_b128 v[160:163], v202
	ds_read_b128 v[164:167], v202 offset:1024
	ds_read_b128 v[168:171], v202 offset:2048
	ds_read_b128 v[172:175], v202 offset:3072
	ds_read_b128 v[208:211], v203
	ds_read_b128 v[212:215], v203 offset:1024
	ds_read_b128 v[218:221], v203 offset:2048
	ds_read_b128 v[222:225], v203 offset:3072
	s_add_i32 s15, s14, 2
	s_add_u32 s10, s12, s6
	s_addc_u32 s11, s13, s7
	s_cmpk_eq_i32 s6, 0x700
	s_cselect_b32 s16, s85, s9
	s_cselect_b32 s17, s84, s8
	s_cselect_b32 s86, 0, s15
	s_cselect_b32 s11, s57, s11
	s_cselect_b32 s10, s56, s10
	v_lshl_add_u64 v[192:193], v[156:157], 0, s[6:7]
	s_add_i32 m0, s39, 0xc000
	ds_read_b128 v[226:229], v204
	ds_read_b128 v[230:233], v204 offset:1024
	ds_read_b128 v[234:237], v204 offset:2048
	ds_read_b128 v[238:241], v204 offset:3072
	ds_read_b128 v[242:245], v204 offset:4096
	ds_read_b128 v[246:249], v204 offset:5120
	ds_read_b128 v[250:253], v204 offset:6144
	ds_read_b128 v[186:189], v204 offset:7168
	global_load_lds_dwordx4 v[192:193], off
	v_lshl_add_u64 v[192:193], v[158:159], 0, s[6:7]
	s_add_i32 m0, s39, 0xe000
	s_nop 0
	global_load_lds_dwordx4 v[192:193], off
	s_waitcnt vmcnt(8)
	s_waitcnt lgkmcnt(0)
	s_barrier
	s_setprio 1
	v_mfma_f32_16x16x32_bf16 v[124:127], v[160:163], v[226:229], v[124:127]
	v_mfma_f32_16x16x32_bf16 v[120:123], v[168:171], v[226:229], v[120:123]
	v_mfma_f32_16x16x32_bf16 v[108:111], v[160:163], v[234:237], v[108:111]
	v_mfma_f32_16x16x32_bf16 v[104:107], v[168:171], v[234:237], v[104:107]
	v_mfma_f32_16x16x32_bf16 v[92:95], v[160:163], v[242:245], v[92:95]
	v_mfma_f32_16x16x32_bf16 v[88:91], v[168:171], v[242:245], v[88:91]
	v_mfma_f32_16x16x32_bf16 v[76:79], v[160:163], v[250:253], v[76:79]
	v_mfma_f32_16x16x32_bf16 v[72:75], v[168:171], v[250:253], v[72:75]
	v_mfma_f32_16x16x32_bf16 v[124:127], v[164:167], v[230:233], v[124:127]
	v_mfma_f32_16x16x32_bf16 v[120:123], v[172:175], v[230:233], v[120:123]
	v_mfma_f32_16x16x32_bf16 v[108:111], v[164:167], v[238:241], v[108:111]
	v_mfma_f32_16x16x32_bf16 v[104:107], v[172:175], v[238:241], v[104:107]
	v_mfma_f32_16x16x32_bf16 v[92:95], v[164:167], v[246:249], v[92:95]
	v_mfma_f32_16x16x32_bf16 v[88:91], v[172:175], v[246:249], v[88:91]
	v_mfma_f32_16x16x32_bf16 v[76:79], v[164:167], v[186:189], v[76:79]
	v_mfma_f32_16x16x32_bf16 v[72:75], v[172:175], v[186:189], v[72:75]
	v_mfma_f32_16x16x32_bf16 v[116:119], v[208:211], v[226:229], v[116:119]
	v_mfma_f32_16x16x32_bf16 v[112:115], v[218:221], v[226:229], v[112:115]
	v_mfma_f32_16x16x32_bf16 v[100:103], v[208:211], v[234:237], v[100:103]
	v_mfma_f32_16x16x32_bf16 v[96:99], v[218:221], v[234:237], v[96:99]
	v_mfma_f32_16x16x32_bf16 v[84:87], v[208:211], v[242:245], v[84:87]
	v_mfma_f32_16x16x32_bf16 v[80:83], v[218:221], v[242:245], v[80:83]
	v_mfma_f32_16x16x32_bf16 v[68:71], v[208:211], v[250:253], v[68:71]
	v_mfma_f32_16x16x32_bf16 v[64:67], v[218:221], v[250:253], v[64:67]
	v_mfma_f32_16x16x32_bf16 v[116:119], v[212:215], v[230:233], v[116:119]
	v_mfma_f32_16x16x32_bf16 v[112:115], v[222:225], v[230:233], v[112:115]
	v_mfma_f32_16x16x32_bf16 v[100:103], v[212:215], v[238:241], v[100:103]
	v_mfma_f32_16x16x32_bf16 v[96:99], v[222:225], v[238:241], v[96:99]
	v_mfma_f32_16x16x32_bf16 v[84:87], v[212:215], v[246:249], v[84:87]
	v_mfma_f32_16x16x32_bf16 v[80:83], v[222:225], v[246:249], v[80:83]
	v_mfma_f32_16x16x32_bf16 v[68:71], v[212:215], v[186:189], v[68:71]
	v_mfma_f32_16x16x32_bf16 v[64:67], v[222:225], v[186:189], v[64:67]
	s_setprio 0
	s_barrier
	s_add_i32 s18, s94, s97
	v_lshl_add_u64 v[192:193], s[10:11], 0, v[132:133]
	s_mov_b32 m0, s18
	ds_read_b128 v[186:189], v204 offset:16384
	ds_read_b128 v[226:229], v204 offset:17408
	ds_read_b128 v[230:233], v204 offset:18432
	ds_read_b128 v[234:237], v204 offset:19456
	ds_read_b128 v[238:241], v204 offset:20480
	ds_read_b128 v[242:245], v204 offset:21504
	ds_read_b128 v[246:249], v204 offset:22528
	ds_read_b128 v[250:253], v204 offset:23552
	global_load_lds_dwordx4 v[192:193], off
	s_add_i32 m0, s18, 0x2000
	s_add_u32 s18, s10, 0x40000
	v_lshl_add_u64 v[196:197], s[10:11], 0, v[136:137]
	s_addc_u32 s19, s11, 0
	s_add_i32 s20, s95, s97
	global_load_lds_dwordx4 v[196:197], off
	v_lshl_add_u64 v[176:177], s[18:19], 0, v[132:133]
	s_mov_b32 m0, s20
	s_nop 0
	global_load_lds_dwordx4 v[176:177], off
	v_lshl_add_u64 v[176:177], s[18:19], 0, v[136:137]
	s_add_i32 m0, s20, 0x2000
	s_lshl_b64 s[18:19], s[86:87], 7
	s_add_u32 s18, s17, s18
	s_addc_u32 s19, s16, s19
	global_load_lds_dwordx4 v[176:177], off
	v_lshl_add_u64 v[176:177], s[18:19], 0, v[130:131]
	s_mov_b32 m0, s39
	s_nop 0
	global_load_lds_dwordx4 v[176:177], off
	v_lshl_add_u64 v[176:177], s[18:19], 0, v[134:135]
	s_mov_b32 m0, s91
	s_nop 0
	global_load_lds_dwordx4 v[176:177], off
	s_waitcnt vmcnt(8)
	s_waitcnt lgkmcnt(0)
	s_barrier
	s_setprio 1
	v_mfma_f32_16x16x32_bf16 v[60:63], v[160:163], v[186:189], v[60:63]
	v_mfma_f32_16x16x32_bf16 v[56:59], v[168:171], v[186:189], v[56:59]
	v_mfma_f32_16x16x32_bf16 v[44:47], v[160:163], v[230:233], v[44:47]
	v_mfma_f32_16x16x32_bf16 v[40:43], v[168:171], v[230:233], v[40:43]
	v_mfma_f32_16x16x32_bf16 v[28:31], v[160:163], v[238:241], v[28:31]
	v_mfma_f32_16x16x32_bf16 v[24:27], v[168:171], v[238:241], v[24:27]
	v_mfma_f32_16x16x32_bf16 v[12:15], v[160:163], v[246:249], v[12:15]
	v_mfma_f32_16x16x32_bf16 v[8:11], v[168:171], v[246:249], v[8:11]
	v_mfma_f32_16x16x32_bf16 v[60:63], v[164:167], v[226:229], v[60:63]
	v_mfma_f32_16x16x32_bf16 v[56:59], v[172:175], v[226:229], v[56:59]
	v_mfma_f32_16x16x32_bf16 v[44:47], v[164:167], v[234:237], v[44:47]
	v_mfma_f32_16x16x32_bf16 v[40:43], v[172:175], v[234:237], v[40:43]
	v_mfma_f32_16x16x32_bf16 v[28:31], v[164:167], v[242:245], v[28:31]
	v_mfma_f32_16x16x32_bf16 v[24:27], v[172:175], v[242:245], v[24:27]
	v_mfma_f32_16x16x32_bf16 v[12:15], v[164:167], v[250:253], v[12:15]
	v_mfma_f32_16x16x32_bf16 v[8:11], v[172:175], v[250:253], v[8:11]
	v_mfma_f32_16x16x32_bf16 v[52:55], v[208:211], v[186:189], v[52:55]
	v_mfma_f32_16x16x32_bf16 v[48:51], v[218:221], v[186:189], v[48:51]
	v_mfma_f32_16x16x32_bf16 v[36:39], v[208:211], v[230:233], v[36:39]
	v_mfma_f32_16x16x32_bf16 v[32:35], v[218:221], v[230:233], v[32:35]
	v_mfma_f32_16x16x32_bf16 v[20:23], v[208:211], v[238:241], v[20:23]
	v_mfma_f32_16x16x32_bf16 v[16:19], v[218:221], v[238:241], v[16:19]
	v_mfma_f32_16x16x32_bf16 v[4:7], v[208:211], v[246:249], v[4:7]
	v_mfma_f32_16x16x32_bf16 v[0:3], v[218:221], v[246:249], v[0:3]
	v_mfma_f32_16x16x32_bf16 v[52:55], v[212:215], v[226:229], v[52:55]
	v_mfma_f32_16x16x32_bf16 v[48:51], v[222:225], v[226:229], v[48:51]
	v_mfma_f32_16x16x32_bf16 v[36:39], v[212:215], v[234:237], v[36:39]
	v_mfma_f32_16x16x32_bf16 v[32:35], v[222:225], v[234:237], v[32:35]
	v_mfma_f32_16x16x32_bf16 v[20:23], v[212:215], v[242:245], v[20:23]
	v_mfma_f32_16x16x32_bf16 v[16:19], v[222:225], v[242:245], v[16:19]
	v_mfma_f32_16x16x32_bf16 v[4:7], v[212:215], v[250:253], v[4:7]
	v_mfma_f32_16x16x32_bf16 v[0:3], v[222:225], v[250:253], v[0:3]
	s_setprio 0
	s_barrier
	s_add_i32 s20, 0, 0x18000
	v_add_u32_e32 v138, s20, v179
	s_add_i32 s21, 0, 0x1c000
	ds_read_b128 v[160:163], v138
	ds_read_b128 v[164:167], v138 offset:1024
	ds_read_b128 v[168:171], v138 offset:2048
	ds_read_b128 v[172:175], v138 offset:3072
	v_add_u32_e32 v138, s21, v179
	ds_read_b128 v[186:189], v138
	ds_read_b128 v[208:211], v138 offset:1024
	ds_read_b128 v[212:215], v138 offset:2048
	ds_read_b128 v[218:221], v138 offset:3072
	s_add_u32 s18, s18, 0x40000
	s_addc_u32 s19, s19, 0
	s_mov_b32 m0, s33
	v_lshl_add_u64 v[176:177], s[18:19], 0, v[130:131]
	ds_read_b128 v[222:225], v204 offset:32768
	ds_read_b128 v[226:229], v204 offset:33792
	ds_read_b128 v[230:233], v204 offset:34816
	ds_read_b128 v[234:237], v204 offset:35840
	ds_read_b128 v[238:241], v204 offset:36864
	ds_read_b128 v[242:245], v204 offset:37888
	ds_read_b128 v[246:249], v204 offset:38912
	ds_read_b128 v[250:253], v204 offset:39936
	global_load_lds_dwordx4 v[176:177], off
	v_lshl_add_u64 v[176:177], s[18:19], 0, v[134:135]
	s_mov_b32 m0, s58
	s_nop 0
	global_load_lds_dwordx4 v[176:177], off
	s_waitcnt vmcnt(8)
	s_waitcnt lgkmcnt(0)
	s_barrier
	s_setprio 1
	v_mfma_f32_16x16x32_bf16 v[124:127], v[160:163], v[222:225], v[124:127]
	v_mfma_f32_16x16x32_bf16 v[120:123], v[168:171], v[222:225], v[120:123]
	v_mfma_f32_16x16x32_bf16 v[108:111], v[160:163], v[230:233], v[108:111]
	v_mfma_f32_16x16x32_bf16 v[104:107], v[168:171], v[230:233], v[104:107]
	v_mfma_f32_16x16x32_bf16 v[92:95], v[160:163], v[238:241], v[92:95]
	v_mfma_f32_16x16x32_bf16 v[88:91], v[168:171], v[238:241], v[88:91]
	v_mfma_f32_16x16x32_bf16 v[76:79], v[160:163], v[246:249], v[76:79]
	v_mfma_f32_16x16x32_bf16 v[72:75], v[168:171], v[246:249], v[72:75]
	v_mfma_f32_16x16x32_bf16 v[124:127], v[164:167], v[226:229], v[124:127]
	v_mfma_f32_16x16x32_bf16 v[120:123], v[172:175], v[226:229], v[120:123]
	v_mfma_f32_16x16x32_bf16 v[108:111], v[164:167], v[234:237], v[108:111]
	v_mfma_f32_16x16x32_bf16 v[104:107], v[172:175], v[234:237], v[104:107]
	v_mfma_f32_16x16x32_bf16 v[92:95], v[164:167], v[242:245], v[92:95]
	v_mfma_f32_16x16x32_bf16 v[88:91], v[172:175], v[242:245], v[88:91]
	v_mfma_f32_16x16x32_bf16 v[76:79], v[164:167], v[250:253], v[76:79]
	v_mfma_f32_16x16x32_bf16 v[72:75], v[172:175], v[250:253], v[72:75]
	v_mfma_f32_16x16x32_bf16 v[116:119], v[186:189], v[222:225], v[116:119]
	v_mfma_f32_16x16x32_bf16 v[112:115], v[212:215], v[222:225], v[112:115]
	v_mfma_f32_16x16x32_bf16 v[100:103], v[186:189], v[230:233], v[100:103]
	v_mfma_f32_16x16x32_bf16 v[96:99], v[212:215], v[230:233], v[96:99]
	v_mfma_f32_16x16x32_bf16 v[84:87], v[186:189], v[238:241], v[84:87]
	v_mfma_f32_16x16x32_bf16 v[80:83], v[212:215], v[238:241], v[80:83]
	v_mfma_f32_16x16x32_bf16 v[68:71], v[186:189], v[246:249], v[68:71]
	v_mfma_f32_16x16x32_bf16 v[64:67], v[212:215], v[246:249], v[64:67]
	v_mfma_f32_16x16x32_bf16 v[116:119], v[208:211], v[226:229], v[116:119]
	v_mfma_f32_16x16x32_bf16 v[112:115], v[218:221], v[226:229], v[112:115]
	v_mfma_f32_16x16x32_bf16 v[100:103], v[208:211], v[234:237], v[100:103]
	v_mfma_f32_16x16x32_bf16 v[96:99], v[218:221], v[234:237], v[96:99]
	v_mfma_f32_16x16x32_bf16 v[84:87], v[208:211], v[242:245], v[84:87]
	v_mfma_f32_16x16x32_bf16 v[80:83], v[218:221], v[242:245], v[80:83]
	v_mfma_f32_16x16x32_bf16 v[68:71], v[208:211], v[250:253], v[68:71]
	v_mfma_f32_16x16x32_bf16 v[64:67], v[218:221], v[250:253], v[64:67]
	s_setprio 0
	s_barrier
	s_add_i32 s18, s20, s97
	v_lshl_add_u64 v[176:177], v[192:193], 0, s[64:65]
	s_mov_b32 m0, s18
	ds_read_b128 v[222:225], v204 offset:49152
	ds_read_b128 v[226:229], v204 offset:50176
	ds_read_b128 v[230:233], v204 offset:51200
	ds_read_b128 v[234:237], v204 offset:52224
	ds_read_b128 v[238:241], v204 offset:53248
	ds_read_b128 v[242:245], v204 offset:54272
	ds_read_b128 v[246:249], v204 offset:55296
	ds_read_b128 v[250:253], v204 offset:56320
	global_load_lds_dwordx4 v[176:177], off
	s_add_i32 m0, s18, 0x2000
	s_add_u32 s10, s10, 0x40080
	v_lshl_add_u64 v[176:177], v[196:197], 0, s[64:65]
	s_addc_u32 s11, s11, 0
	s_add_i32 s18, s21, s97
	global_load_lds_dwordx4 v[176:177], off
	v_lshl_add_u64 v[176:177], s[10:11], 0, v[132:133]
	s_mov_b32 m0, s18
	s_or_b32 s86, s86, 1
	global_load_lds_dwordx4 v[176:177], off
	v_lshl_add_u64 v[176:177], s[10:11], 0, v[136:137]
	s_add_i32 m0, s18, 0x2000
	s_lshl_b64 s[10:11], s[86:87], 7
	s_add_u32 s10, s17, s10
	s_addc_u32 s11, s16, s11
	global_load_lds_dwordx4 v[176:177], off
	v_lshl_add_u64 v[176:177], s[10:11], 0, v[130:131]
	s_mov_b32 m0, s92
	s_nop 0
	global_load_lds_dwordx4 v[176:177], off
	v_lshl_add_u64 v[176:177], s[10:11], 0, v[134:135]
	s_mov_b32 m0, s93
	s_nop 0
	global_load_lds_dwordx4 v[176:177], off
	s_waitcnt vmcnt(8)
	s_waitcnt lgkmcnt(0)
	s_barrier
	s_setprio 1
	v_mfma_f32_16x16x32_bf16 v[60:63], v[160:163], v[222:225], v[60:63]
	v_mfma_f32_16x16x32_bf16 v[56:59], v[168:171], v[222:225], v[56:59]
	v_mfma_f32_16x16x32_bf16 v[44:47], v[160:163], v[230:233], v[44:47]
	v_mfma_f32_16x16x32_bf16 v[40:43], v[168:171], v[230:233], v[40:43]
	v_mfma_f32_16x16x32_bf16 v[28:31], v[160:163], v[238:241], v[28:31]
	v_mfma_f32_16x16x32_bf16 v[24:27], v[168:171], v[238:241], v[24:27]
	v_mfma_f32_16x16x32_bf16 v[12:15], v[160:163], v[246:249], v[12:15]
	v_mfma_f32_16x16x32_bf16 v[8:11], v[168:171], v[246:249], v[8:11]
	v_mfma_f32_16x16x32_bf16 v[60:63], v[164:167], v[226:229], v[60:63]
	v_mfma_f32_16x16x32_bf16 v[56:59], v[172:175], v[226:229], v[56:59]
	v_mfma_f32_16x16x32_bf16 v[44:47], v[164:167], v[234:237], v[44:47]
	v_mfma_f32_16x16x32_bf16 v[40:43], v[172:175], v[234:237], v[40:43]
	v_mfma_f32_16x16x32_bf16 v[28:31], v[164:167], v[242:245], v[28:31]
	v_mfma_f32_16x16x32_bf16 v[24:27], v[172:175], v[242:245], v[24:27]
	v_mfma_f32_16x16x32_bf16 v[12:15], v[164:167], v[250:253], v[12:15]
	v_mfma_f32_16x16x32_bf16 v[8:11], v[172:175], v[250:253], v[8:11]
	v_mfma_f32_16x16x32_bf16 v[52:55], v[186:189], v[222:225], v[52:55]
	v_mfma_f32_16x16x32_bf16 v[48:51], v[212:215], v[222:225], v[48:51]
	v_mfma_f32_16x16x32_bf16 v[36:39], v[186:189], v[230:233], v[36:39]
	v_mfma_f32_16x16x32_bf16 v[32:35], v[212:215], v[230:233], v[32:35]
	v_mfma_f32_16x16x32_bf16 v[20:23], v[186:189], v[238:241], v[20:23]
	v_mfma_f32_16x16x32_bf16 v[16:19], v[212:215], v[238:241], v[16:19]
	v_mfma_f32_16x16x32_bf16 v[4:7], v[186:189], v[246:249], v[4:7]
	v_mfma_f32_16x16x32_bf16 v[0:3], v[212:215], v[246:249], v[0:3]
	v_mfma_f32_16x16x32_bf16 v[52:55], v[208:211], v[226:229], v[52:55]
	v_mfma_f32_16x16x32_bf16 v[48:51], v[218:221], v[226:229], v[48:51]
	v_mfma_f32_16x16x32_bf16 v[36:39], v[208:211], v[234:237], v[36:39]
	v_mfma_f32_16x16x32_bf16 v[32:35], v[218:221], v[234:237], v[32:35]
	v_mfma_f32_16x16x32_bf16 v[20:23], v[208:211], v[242:245], v[20:23]
	v_mfma_f32_16x16x32_bf16 v[16:19], v[218:221], v[242:245], v[16:19]
	v_mfma_f32_16x16x32_bf16 v[4:7], v[208:211], v[250:253], v[4:7]
	v_mfma_f32_16x16x32_bf16 v[0:3], v[218:221], v[250:253], v[0:3]
	s_setprio 0
	s_barrier
	s_add_u32 s6, s6, 0x100
	s_addc_u32 s7, s7, 0
	s_cmp_gt_u32 s14, 13
	s_mov_b32 s14, s15
	s_cbranch_scc0 .LBB0_124
	s_and_b64 vcc, exec, s[66:67]
	s_cbranch_vccz .LBB0_127
	s_barrier

.LBB0_425:
	s_add_u32 s12, s30, s38
	s_addc_u32 s42, s31, s39
	s_add_u32 s12, s12, 0xfff80080
	s_addc_u32 s65, s42, -1
	s_cmp_eq_u32 s64, 30
	s_cselect_b64 s[42:43], -1, 0
	s_and_b64 s[42:43], s[42:43], exec
	s_cselect_b32 s43, s19, s65
	s_cselect_b32 s42, s21, s12
	s_add_i32 s65, s64, 2
	s_cmp_eq_u32 s64, 30
	s_cselect_b64 s[66:67], -1, 0
	s_and_b64 s[68:69], s[66:67], exec
	s_cselect_b32 s12, 0, s65
	s_and_b64 s[66:67], s[66:67], s[4:5]
	s_and_b64 s[66:67], s[66:67], exec
	s_cselect_b32 s68, s23, s35
	s_cselect_b32 s69, s22, s34
	s_cselect_b32 s66, s27, s37
	s_cselect_b32 s67, s26, s36
	v_lshl_add_u64 v[214:215], s[44:45], 0, v[214:215]
	s_add_i32 m0, s29, 0xc000
	v_lshl_add_u64 v[2:3], s[44:45], 0, v[2:3]
	global_load_lds_dwordx4 v[214:215], off
	s_add_i32 m0, s29, 0xe000
	s_nop 0
	global_load_lds_dwordx4 v[2:3], off
	s_waitcnt vmcnt(8)
	s_waitcnt lgkmcnt(0)
	s_barrier
	s_setprio 1
	v_mfma_f32_16x16x32_bf16 v[128:131], v[148:151], v[188:191], v[128:131]
	v_mfma_f32_16x16x32_bf16 v[124:127], v[156:159], v[188:191], v[124:127]
	v_mfma_f32_16x16x32_bf16 v[112:115], v[148:151], v[180:183], v[112:115]
	v_mfma_f32_16x16x32_bf16 v[108:111], v[156:159], v[180:183], v[108:111]
	v_mfma_f32_16x16x32_bf16 v[96:99], v[148:151], v[172:175], v[96:99]
	v_mfma_f32_16x16x32_bf16 v[92:95], v[156:159], v[172:175], v[92:95]
	v_mfma_f32_16x16x32_bf16 v[80:83], v[148:151], v[164:167], v[80:83]
	v_mfma_f32_16x16x32_bf16 v[76:79], v[156:159], v[164:167], v[76:79]
	v_mfma_f32_16x16x32_bf16 v[128:131], v[152:155], v[192:195], v[128:131]
	v_mfma_f32_16x16x32_bf16 v[124:127], v[160:163], v[192:195], v[124:127]
	v_mfma_f32_16x16x32_bf16 v[112:115], v[152:155], v[184:187], v[112:115]
	v_mfma_f32_16x16x32_bf16 v[108:111], v[160:163], v[184:187], v[108:111]
	v_mfma_f32_16x16x32_bf16 v[96:99], v[152:155], v[176:179], v[96:99]
	v_mfma_f32_16x16x32_bf16 v[92:95], v[160:163], v[176:179], v[92:95]
	v_mfma_f32_16x16x32_bf16 v[80:83], v[152:155], v[168:171], v[80:83]
	v_mfma_f32_16x16x32_bf16 v[76:79], v[160:163], v[168:171], v[76:79]
	v_mfma_f32_16x16x32_bf16 v[120:123], v[132:135], v[188:191], v[120:123]
	v_mfma_f32_16x16x32_bf16 v[116:119], v[140:143], v[188:191], v[116:119]
	v_mfma_f32_16x16x32_bf16 v[104:107], v[132:135], v[180:183], v[104:107]
	v_mfma_f32_16x16x32_bf16 v[100:103], v[140:143], v[180:183], v[100:103]
	v_mfma_f32_16x16x32_bf16 v[88:91], v[132:135], v[172:175], v[88:91]
	v_mfma_f32_16x16x32_bf16 v[84:87], v[140:143], v[172:175], v[84:87]
	v_mfma_f32_16x16x32_bf16 v[72:75], v[132:135], v[164:167], v[72:75]
	v_mfma_f32_16x16x32_bf16 v[68:71], v[140:143], v[164:167], v[68:71]
	v_mfma_f32_16x16x32_bf16 v[120:123], v[136:139], v[192:195], v[120:123]
	v_mfma_f32_16x16x32_bf16 v[116:119], v[144:147], v[192:195], v[116:119]
	v_mfma_f32_16x16x32_bf16 v[104:107], v[136:139], v[184:187], v[104:107]
	v_mfma_f32_16x16x32_bf16 v[100:103], v[144:147], v[184:187], v[100:103]
	v_mfma_f32_16x16x32_bf16 v[88:91], v[136:139], v[176:179], v[88:91]
	v_mfma_f32_16x16x32_bf16 v[84:87], v[144:147], v[176:179], v[84:87]
	v_mfma_f32_16x16x32_bf16 v[72:75], v[136:139], v[168:171], v[72:75]
	v_mfma_f32_16x16x32_bf16 v[68:71], v[144:147], v[168:171], v[68:71]
	s_setprio 0
	s_barrier
	s_mov_b32 m0, s47
	v_lshl_add_u64 v[214:215], s[42:43], 0, v[198:199]
	s_add_u32 s44, s42, 0x80000
	ds_read_b128 v[164:167], v219 offset:16384
	ds_read_b128 v[168:171], v219 offset:17408
	ds_read_b128 v[172:175], v219 offset:18432
	ds_read_b128 v[176:179], v219 offset:19456
	ds_read_b128 v[180:183], v219 offset:20480
	ds_read_b128 v[184:187], v219 offset:21504
	ds_read_b128 v[188:191], v219 offset:22528
	ds_read_b128 v[192:195], v219 offset:23552
	global_load_lds_dwordx4 v[214:215], off
	v_lshl_add_u64 v[220:221], s[42:43], 0, v[202:203]
	s_mov_b32 m0, s48
	s_addc_u32 s45, s43, 0
	global_load_lds_dwordx4 v[220:221], off
	v_lshl_add_u64 v[2:3], s[44:45], 0, v[198:199]
	s_mov_b32 m0, s49
	s_add_i32 s70, s12, -8
	global_load_lds_dwordx4 v[2:3], off
	v_lshl_add_u64 v[2:3], s[44:45], 0, v[202:203]
	s_lshl_b64 s[44:45], s[12:13], 7
	s_add_u32 s71, s69, s44
	s_addc_u32 s72, s68, s45
	s_lshl_b32 s44, s70, 19
	s_add_u32 s73, s67, s44
	s_addc_u32 s74, s66, 0
	s_add_i32 s75, 0, 0x18000
	s_add_i32 s76, 0, 0x1c000
	s_add_u32 s77, s71, 0x80000
	s_addc_u32 s84, s72, 0
	s_add_u32 s85, s73, 0x800
	s_addc_u32 s86, s74, 0
	s_cmp_lt_u32 s70, 16
	s_cselect_b64 vcc, -1, 0
	s_and_b64 s[44:45], vcc, exec
	s_mov_b32 m0, s50
	v_cndmask_b32_e32 v222, v196, v204, vcc
	v_mov_b32_e32 v223, v1
	s_cselect_b32 s45, s74, s72
	s_cselect_b32 s44, s73, s71
	global_load_lds_dwordx4 v[2:3], off
	v_cndmask_b32_e32 v0, v200, v206, vcc
	v_lshl_add_u64 v[2:3], s[44:45], 0, v[222:223]
	s_mov_b32 m0, s29
	s_nop 0
	global_load_lds_dwordx4 v[2:3], off
	v_lshl_add_u64 v[2:3], s[44:45], 0, v[0:1]
	s_mov_b32 m0, s51
	s_nop 0
	global_load_lds_dwordx4 v[2:3], off
	s_waitcnt vmcnt(8)
	s_waitcnt lgkmcnt(0)
	s_barrier
	s_setprio 1
	v_mfma_f32_16x16x32_bf16 v[64:67], v[148:151], v[164:167], v[64:67]
	v_mfma_f32_16x16x32_bf16 v[60:63], v[156:159], v[164:167], v[60:63]
	v_mfma_f32_16x16x32_bf16 v[48:51], v[148:151], v[172:175], v[48:51]
	v_mfma_f32_16x16x32_bf16 v[44:47], v[156:159], v[172:175], v[44:47]
	v_mfma_f32_16x16x32_bf16 v[32:35], v[148:151], v[180:183], v[32:35]
	v_mfma_f32_16x16x32_bf16 v[28:31], v[156:159], v[180:183], v[28:31]
	v_mfma_f32_16x16x32_bf16 v[16:19], v[148:151], v[188:191], v[16:19]
	v_mfma_f32_16x16x32_bf16 v[12:15], v[156:159], v[188:191], v[12:15]
	v_mfma_f32_16x16x32_bf16 v[64:67], v[152:155], v[168:171], v[64:67]
	v_mfma_f32_16x16x32_bf16 v[60:63], v[160:163], v[168:171], v[60:63]
	v_mfma_f32_16x16x32_bf16 v[48:51], v[152:155], v[176:179], v[48:51]
	v_mfma_f32_16x16x32_bf16 v[44:47], v[160:163], v[176:179], v[44:47]
	v_mfma_f32_16x16x32_bf16 v[32:35], v[152:155], v[184:187], v[32:35]
	v_mfma_f32_16x16x32_bf16 v[28:31], v[160:163], v[184:187], v[28:31]
	v_mfma_f32_16x16x32_bf16 v[16:19], v[152:155], v[192:195], v[16:19]
	v_mfma_f32_16x16x32_bf16 v[12:15], v[160:163], v[192:195], v[12:15]
	v_mfma_f32_16x16x32_bf16 v[56:59], v[132:135], v[164:167], v[56:59]
	v_mfma_f32_16x16x32_bf16 v[52:55], v[140:143], v[164:167], v[52:55]
	v_mfma_f32_16x16x32_bf16 v[40:43], v[132:135], v[172:175], v[40:43]
	v_mfma_f32_16x16x32_bf16 v[36:39], v[140:143], v[172:175], v[36:39]
	v_mfma_f32_16x16x32_bf16 v[24:27], v[132:135], v[180:183], v[24:27]
	v_mfma_f32_16x16x32_bf16 v[20:23], v[140:143], v[180:183], v[20:23]
	v_mfma_f32_16x16x32_bf16 v[8:11], v[132:135], v[188:191], v[8:11]
	v_mfma_f32_16x16x32_bf16 v[2:5], v[140:143], v[188:191], v[4:7]
	v_mfma_f32_16x16x32_bf16 v[56:59], v[136:139], v[168:171], v[56:59]
	v_mfma_f32_16x16x32_bf16 v[52:55], v[144:147], v[168:171], v[52:55]
	v_mfma_f32_16x16x32_bf16 v[40:43], v[136:139], v[176:179], v[40:43]
	v_mfma_f32_16x16x32_bf16 v[36:39], v[144:147], v[176:179], v[36:39]
	v_mfma_f32_16x16x32_bf16 v[24:27], v[136:139], v[184:187], v[24:27]
	v_mfma_f32_16x16x32_bf16 v[20:23], v[144:147], v[184:187], v[20:23]
	v_mfma_f32_16x16x32_bf16 v[8:11], v[136:139], v[192:195], v[8:11]
	v_mfma_f32_16x16x32_bf16 v[2:5], v[144:147], v[192:195], v[2:5]
	s_setprio 0
	s_barrier
	v_add_u32_e32 v6, s75, v217
	ds_read_b128 v[148:151], v6
	ds_read_b128 v[152:155], v6 offset:1024
	ds_read_b128 v[156:159], v6 offset:2048
	ds_read_b128 v[160:163], v6 offset:3072
	v_add_u32_e32 v6, s76, v217
	ds_read_b128 v[132:135], v6
	ds_read_b128 v[136:139], v6 offset:1024
	ds_read_b128 v[140:143], v6 offset:2048
	ds_read_b128 v[144:147], v6 offset:3072
	s_cselect_b32 s45, s86, s84
	s_cselect_b32 s44, s85, s77
	s_mov_b32 m0, s52
	v_lshl_add_u64 v[6:7], s[44:45], 0, v[222:223]
	ds_read_b128 v[164:167], v219 offset:32768
	ds_read_b128 v[168:171], v219 offset:33792
	ds_read_b128 v[172:175], v219 offset:34816
	ds_read_b128 v[176:179], v219 offset:35840
	ds_read_b128 v[180:183], v219 offset:36864
	ds_read_b128 v[184:187], v219 offset:37888
	ds_read_b128 v[188:191], v219 offset:38912
	ds_read_b128 v[192:195], v219 offset:39936
	global_load_lds_dwordx4 v[6:7], off
	v_lshl_add_u64 v[6:7], s[44:45], 0, v[0:1]
	s_mov_b32 m0, s53
	s_nop 0
	global_load_lds_dwordx4 v[6:7], off
	s_waitcnt vmcnt(8)
	s_waitcnt lgkmcnt(0)
	s_barrier
	s_setprio 1
	v_mfma_f32_16x16x32_bf16 v[128:131], v[148:151], v[164:167], v[128:131]
	v_mfma_f32_16x16x32_bf16 v[124:127], v[156:159], v[164:167], v[124:127]
	v_mfma_f32_16x16x32_bf16 v[112:115], v[148:151], v[172:175], v[112:115]
	v_mfma_f32_16x16x32_bf16 v[108:111], v[156:159], v[172:175], v[108:111]
	v_mfma_f32_16x16x32_bf16 v[96:99], v[148:151], v[180:183], v[96:99]
	v_mfma_f32_16x16x32_bf16 v[92:95], v[156:159], v[180:183], v[92:95]
	v_mfma_f32_16x16x32_bf16 v[80:83], v[148:151], v[188:191], v[80:83]
	v_mfma_f32_16x16x32_bf16 v[76:79], v[156:159], v[188:191], v[76:79]
	v_mfma_f32_16x16x32_bf16 v[128:131], v[152:155], v[168:171], v[128:131]
	v_mfma_f32_16x16x32_bf16 v[124:127], v[160:163], v[168:171], v[124:127]
	v_mfma_f32_16x16x32_bf16 v[112:115], v[152:155], v[176:179], v[112:115]
	v_mfma_f32_16x16x32_bf16 v[108:111], v[160:163], v[176:179], v[108:111]
	v_mfma_f32_16x16x32_bf16 v[96:99], v[152:155], v[184:187], v[96:99]
	v_mfma_f32_16x16x32_bf16 v[92:95], v[160:163], v[184:187], v[92:95]
	v_mfma_f32_16x16x32_bf16 v[80:83], v[152:155], v[192:195], v[80:83]
	v_mfma_f32_16x16x32_bf16 v[76:79], v[160:163], v[192:195], v[76:79]
	v_mfma_f32_16x16x32_bf16 v[120:123], v[132:135], v[164:167], v[120:123]
	v_mfma_f32_16x16x32_bf16 v[116:119], v[140:143], v[164:167], v[116:119]
	v_mfma_f32_16x16x32_bf16 v[104:107], v[132:135], v[172:175], v[104:107]
	v_mfma_f32_16x16x32_bf16 v[100:103], v[140:143], v[172:175], v[100:103]
	v_mfma_f32_16x16x32_bf16 v[88:91], v[132:135], v[180:183], v[88:91]
	v_mfma_f32_16x16x32_bf16 v[84:87], v[140:143], v[180:183], v[84:87]
	v_mfma_f32_16x16x32_bf16 v[72:75], v[132:135], v[188:191], v[72:75]
	v_mfma_f32_16x16x32_bf16 v[68:71], v[140:143], v[188:191], v[68:71]
	v_mfma_f32_16x16x32_bf16 v[120:123], v[136:139], v[168:171], v[120:123]
	v_mfma_f32_16x16x32_bf16 v[116:119], v[144:147], v[168:171], v[116:119]
	v_mfma_f32_16x16x32_bf16 v[104:107], v[136:139], v[176:179], v[104:107]
	v_mfma_f32_16x16x32_bf16 v[100:103], v[144:147], v[176:179], v[100:103]
	v_mfma_f32_16x16x32_bf16 v[88:91], v[136:139], v[184:187], v[88:91]
	v_mfma_f32_16x16x32_bf16 v[84:87], v[144:147], v[184:187], v[84:87]
	v_mfma_f32_16x16x32_bf16 v[72:75], v[136:139], v[192:195], v[72:75]
	v_mfma_f32_16x16x32_bf16 v[68:71], v[144:147], v[192:195], v[68:71]
	s_setprio 0
	s_barrier
	s_add_i32 s44, s75, s33
	v_lshl_add_u64 v[6:7], v[214:215], 0, s[14:15]
	s_mov_b32 m0, s44
	ds_read_b128 v[188:191], v219 offset:49152
	ds_read_b128 v[192:195], v219 offset:50176
	ds_read_b128 v[180:183], v219 offset:51200
	ds_read_b128 v[184:187], v219 offset:52224
	ds_read_b128 v[172:175], v219 offset:53248
	ds_read_b128 v[176:179], v219 offset:54272
	ds_read_b128 v[164:167], v219 offset:55296
	ds_read_b128 v[168:171], v219 offset:56320
	global_load_lds_dwordx4 v[6:7], off
	s_add_i32 m0, s44, 0x2000
	s_add_u32 s42, s42, 0x80080
	v_lshl_add_u64 v[6:7], v[220:221], 0, s[14:15]
	s_addc_u32 s43, s43, 0
	s_add_i32 s44, s76, s33
	global_load_lds_dwordx4 v[6:7], off
	v_lshl_add_u64 v[6:7], s[42:43], 0, v[198:199]
	s_mov_b32 m0, s44
	s_add_i32 s70, s12, -7
	global_load_lds_dwordx4 v[6:7], off
	v_lshl_add_u64 v[6:7], s[42:43], 0, v[202:203]
	s_add_i32 m0, s44, 0x2000
	s_cmp_gt_u32 s70, 15
	global_load_lds_dwordx4 v[6:7], off
	s_mov_b64 s[44:45], -1
	s_cbranch_scc0 .LBB0_427
	s_or_b32 s12, s12, 1
	s_lshl_b64 s[42:43], s[12:13], 7
	s_add_u32 s42, s69, s42
	s_addc_u32 s43, s68, s43
	s_mov_b64 s[44:45], 0

.LBB0_429:
	s_mov_b32 m0, s55
	v_lshl_add_u64 v[214:215], s[42:43], 0, v[214:215]
	global_load_lds_dwordx4 v[214:215], off
	v_lshl_add_u64 v[6:7], s[42:43], 0, v[6:7]
	s_mov_b32 m0, s56
	s_nop 0
	global_load_lds_dwordx4 v[6:7], off
	s_waitcnt vmcnt(8)
	s_waitcnt lgkmcnt(0)
	s_barrier
	s_setprio 1
	v_mfma_f32_16x16x32_bf16 v[64:67], v[148:151], v[188:191], v[64:67]
	v_mfma_f32_16x16x32_bf16 v[60:63], v[156:159], v[188:191], v[60:63]
	v_mfma_f32_16x16x32_bf16 v[48:51], v[148:151], v[180:183], v[48:51]
	v_mfma_f32_16x16x32_bf16 v[44:47], v[156:159], v[180:183], v[44:47]
	v_mfma_f32_16x16x32_bf16 v[32:35], v[148:151], v[172:175], v[32:35]
	v_mfma_f32_16x16x32_bf16 v[28:31], v[156:159], v[172:175], v[28:31]
	v_mfma_f32_16x16x32_bf16 v[16:19], v[148:151], v[164:167], v[16:19]
	v_mfma_f32_16x16x32_bf16 v[12:15], v[156:159], v[164:167], v[12:15]
	v_mfma_f32_16x16x32_bf16 v[64:67], v[152:155], v[192:195], v[64:67]
	v_mfma_f32_16x16x32_bf16 v[60:63], v[160:163], v[192:195], v[60:63]
	v_mfma_f32_16x16x32_bf16 v[48:51], v[152:155], v[184:187], v[48:51]
	v_mfma_f32_16x16x32_bf16 v[44:47], v[160:163], v[184:187], v[44:47]
	v_mfma_f32_16x16x32_bf16 v[32:35], v[152:155], v[176:179], v[32:35]
	v_mfma_f32_16x16x32_bf16 v[28:31], v[160:163], v[176:179], v[28:31]
	v_mfma_f32_16x16x32_bf16 v[16:19], v[152:155], v[168:171], v[16:19]
	v_mfma_f32_16x16x32_bf16 v[12:15], v[160:163], v[168:171], v[12:15]
	v_mfma_f32_16x16x32_bf16 v[56:59], v[132:135], v[188:191], v[56:59]
	v_mfma_f32_16x16x32_bf16 v[52:55], v[140:143], v[188:191], v[52:55]
	v_mfma_f32_16x16x32_bf16 v[40:43], v[132:135], v[180:183], v[40:43]
	v_mfma_f32_16x16x32_bf16 v[36:39], v[140:143], v[180:183], v[36:39]
	v_mfma_f32_16x16x32_bf16 v[24:27], v[132:135], v[172:175], v[24:27]
	v_mfma_f32_16x16x32_bf16 v[20:23], v[140:143], v[172:175], v[20:23]
	v_mfma_f32_16x16x32_bf16 v[6:9], v[132:135], v[164:167], v[8:11]
	v_mfma_f32_16x16x32_bf16 v[2:5], v[140:143], v[164:167], v[2:5]
	v_mfma_f32_16x16x32_bf16 v[56:59], v[136:139], v[192:195], v[56:59]
	v_mfma_f32_16x16x32_bf16 v[52:55], v[144:147], v[192:195], v[52:55]
	v_mfma_f32_16x16x32_bf16 v[40:43], v[136:139], v[184:187], v[40:43]
	v_mfma_f32_16x16x32_bf16 v[36:39], v[144:147], v[184:187], v[36:39]
	v_mfma_f32_16x16x32_bf16 v[24:27], v[136:139], v[176:179], v[24:27]
	v_mfma_f32_16x16x32_bf16 v[20:23], v[144:147], v[176:179], v[20:23]
	v_mfma_f32_16x16x32_bf16 v[8:11], v[136:139], v[168:171], v[6:9]
	v_mfma_f32_16x16x32_bf16 v[4:7], v[144:147], v[168:171], v[2:5]
	s_setprio 0
	s_barrier
	s_add_u32 s38, s38, 0x100
	s_addc_u32 s39, s39, 0
	s_add_i32 s63, s63, 0x100000
	s_cmp_gt_u32 s64, 29
	s_cbranch_scc1 .LBB0_408
	s_mov_b32 s64, s65
	s_cmp_lt_i32 s64, 24
	s_cbranch_scc1 .LBB0_417
	s_branch .LBB0_416

.LBB0_504:
	s_add_u32 s20, s31, s44
	ds_read_b128 v[132:135], v217
	ds_read_b128 v[136:139], v217 offset:1024
	ds_read_b128 v[140:143], v217 offset:2048
	ds_read_b128 v[144:147], v217 offset:3072
	ds_read_b128 v[148:151], v218
	ds_read_b128 v[152:155], v218 offset:1024
	ds_read_b128 v[156:159], v218 offset:2048
	ds_read_b128 v[160:163], v218 offset:3072
	s_addc_u32 s48, s39, s45
	s_cmpk_eq_i32 s44, 0x700
	s_cselect_b64 s[46:47], -1, 0
	s_and_b64 s[46:47], s[46:47], exec
	s_cselect_b32 s47, s19, s48
	s_cselect_b32 s46, s29, s20
	s_add_i32 s64, s63, 2
	s_cmpk_eq_i32 s44, 0x700
	s_cselect_b64 s[48:49], -1, 0
	s_and_b64 s[66:67], s[48:49], exec
	s_cselect_b32 s20, 0, s64
	s_and_b64 s[48:49], s[48:49], s[6:7]
	s_and_b64 s[48:49], s[48:49], exec
	s_cselect_b32 s48, s35, s43
	s_cselect_b32 s49, s34, s42
	v_lshl_add_u64 v[238:239], v[128:129], 0, s[44:45]
	s_add_i32 m0, s50, 0xc000
	ds_read_b128 v[164:167], v219
	ds_read_b128 v[168:171], v219 offset:1024
	ds_read_b128 v[172:175], v219 offset:2048
	ds_read_b128 v[192:195], v219 offset:3072
	ds_read_b128 v[222:225], v219 offset:4096
	ds_read_b128 v[226:229], v219 offset:5120
	ds_read_b128 v[230:233], v219 offset:6144
	ds_read_b128 v[234:237], v219 offset:7168
	global_load_lds_dwordx4 v[238:239], off
	v_lshl_add_u64 v[238:239], v[130:131], 0, s[44:45]
	s_add_i32 m0, s50, 0xe000
	s_nop 0
	global_load_lds_dwordx4 v[238:239], off
	s_waitcnt vmcnt(8)
	s_waitcnt lgkmcnt(0)
	s_barrier
	s_setprio 1
	v_mfma_f32_16x16x32_bf16 v[124:127], v[132:135], v[164:167], v[124:127]
	v_mfma_f32_16x16x32_bf16 v[120:123], v[140:143], v[164:167], v[120:123]
	v_mfma_f32_16x16x32_bf16 v[108:111], v[132:135], v[172:175], v[108:111]
	v_mfma_f32_16x16x32_bf16 v[104:107], v[140:143], v[172:175], v[104:107]
	v_mfma_f32_16x16x32_bf16 v[92:95], v[132:135], v[222:225], v[92:95]
	v_mfma_f32_16x16x32_bf16 v[88:91], v[140:143], v[222:225], v[88:91]
	v_mfma_f32_16x16x32_bf16 v[76:79], v[132:135], v[230:233], v[76:79]
	v_mfma_f32_16x16x32_bf16 v[72:75], v[140:143], v[230:233], v[72:75]
	v_mfma_f32_16x16x32_bf16 v[124:127], v[136:139], v[168:171], v[124:127]
	v_mfma_f32_16x16x32_bf16 v[120:123], v[144:147], v[168:171], v[120:123]
	v_mfma_f32_16x16x32_bf16 v[108:111], v[136:139], v[192:195], v[108:111]
	v_mfma_f32_16x16x32_bf16 v[104:107], v[144:147], v[192:195], v[104:107]
	v_mfma_f32_16x16x32_bf16 v[92:95], v[136:139], v[226:229], v[92:95]
	v_mfma_f32_16x16x32_bf16 v[88:91], v[144:147], v[226:229], v[88:91]
	v_mfma_f32_16x16x32_bf16 v[76:79], v[136:139], v[234:237], v[76:79]
	v_mfma_f32_16x16x32_bf16 v[72:75], v[144:147], v[234:237], v[72:75]
	v_mfma_f32_16x16x32_bf16 v[116:119], v[148:151], v[164:167], v[116:119]
	v_mfma_f32_16x16x32_bf16 v[112:115], v[156:159], v[164:167], v[112:115]
	v_mfma_f32_16x16x32_bf16 v[100:103], v[148:151], v[172:175], v[100:103]
	v_mfma_f32_16x16x32_bf16 v[96:99], v[156:159], v[172:175], v[96:99]
	v_mfma_f32_16x16x32_bf16 v[84:87], v[148:151], v[222:225], v[84:87]
	v_mfma_f32_16x16x32_bf16 v[80:83], v[156:159], v[222:225], v[80:83]
	v_mfma_f32_16x16x32_bf16 v[68:71], v[148:151], v[230:233], v[68:71]
	v_mfma_f32_16x16x32_bf16 v[64:67], v[156:159], v[230:233], v[64:67]
	v_mfma_f32_16x16x32_bf16 v[116:119], v[152:155], v[168:171], v[116:119]
	v_mfma_f32_16x16x32_bf16 v[112:115], v[160:163], v[168:171], v[112:115]
	v_mfma_f32_16x16x32_bf16 v[100:103], v[152:155], v[192:195], v[100:103]
	v_mfma_f32_16x16x32_bf16 v[96:99], v[160:163], v[192:195], v[96:99]
	v_mfma_f32_16x16x32_bf16 v[84:87], v[152:155], v[226:229], v[84:87]
	v_mfma_f32_16x16x32_bf16 v[80:83], v[160:163], v[226:229], v[80:83]
	v_mfma_f32_16x16x32_bf16 v[68:71], v[152:155], v[234:237], v[68:71]
	v_mfma_f32_16x16x32_bf16 v[64:67], v[160:163], v[234:237], v[64:67]
	s_setprio 0
	s_barrier
	s_add_i32 s65, s58, s33
	v_lshl_add_u64 v[238:239], s[46:47], 0, v[178:179]
	s_mov_b32 m0, s65
	ds_read_b128 v[164:167], v219 offset:16384
	ds_read_b128 v[168:171], v219 offset:17408
	ds_read_b128 v[172:175], v219 offset:18432
	ds_read_b128 v[192:195], v219 offset:19456
	ds_read_b128 v[222:225], v219 offset:20480
	ds_read_b128 v[226:229], v219 offset:21504
	ds_read_b128 v[230:233], v219 offset:22528
	ds_read_b128 v[234:237], v219 offset:23552
	global_load_lds_dwordx4 v[238:239], off
	s_add_i32 m0, s65, 0x2000
	s_add_u32 s66, s46, 0x40000
	v_lshl_add_u64 v[240:241], s[46:47], 0, v[182:183]
	s_addc_u32 s67, s47, 0
	s_add_i32 s65, s59, s33
	global_load_lds_dwordx4 v[240:241], off
	v_lshl_add_u64 v[242:243], s[66:67], 0, v[178:179]
	s_mov_b32 m0, s65
	s_nop 0
	global_load_lds_dwordx4 v[242:243], off
	v_lshl_add_u64 v[242:243], s[66:67], 0, v[182:183]
	s_add_i32 m0, s65, 0x2000
	s_lshl_b64 s[66:67], s[20:21], 7
	s_add_u32 s66, s49, s66
	s_addc_u32 s67, s48, s67
	global_load_lds_dwordx4 v[242:243], off
	v_lshl_add_u64 v[242:243], s[66:67], 0, v[176:177]
	s_mov_b32 m0, s50
	s_nop 0
	global_load_lds_dwordx4 v[242:243], off
	v_lshl_add_u64 v[242:243], s[66:67], 0, v[180:181]
	s_mov_b32 m0, s51
	s_nop 0
	global_load_lds_dwordx4 v[242:243], off
	s_waitcnt vmcnt(8)
	s_waitcnt lgkmcnt(0)
	s_barrier
	s_setprio 1
	v_mfma_f32_16x16x32_bf16 v[60:63], v[132:135], v[164:167], v[60:63]
	v_mfma_f32_16x16x32_bf16 v[56:59], v[140:143], v[164:167], v[56:59]
	v_mfma_f32_16x16x32_bf16 v[44:47], v[132:135], v[172:175], v[44:47]
	v_mfma_f32_16x16x32_bf16 v[40:43], v[140:143], v[172:175], v[40:43]
	v_mfma_f32_16x16x32_bf16 v[28:31], v[132:135], v[222:225], v[28:31]
	v_mfma_f32_16x16x32_bf16 v[24:27], v[140:143], v[222:225], v[24:27]
	v_mfma_f32_16x16x32_bf16 v[12:15], v[132:135], v[230:233], v[12:15]
	v_mfma_f32_16x16x32_bf16 v[8:11], v[140:143], v[230:233], v[8:11]
	v_mfma_f32_16x16x32_bf16 v[60:63], v[136:139], v[168:171], v[60:63]
	v_mfma_f32_16x16x32_bf16 v[56:59], v[144:147], v[168:171], v[56:59]
	v_mfma_f32_16x16x32_bf16 v[44:47], v[136:139], v[192:195], v[44:47]
	v_mfma_f32_16x16x32_bf16 v[40:43], v[144:147], v[192:195], v[40:43]
	v_mfma_f32_16x16x32_bf16 v[28:31], v[136:139], v[226:229], v[28:31]
	v_mfma_f32_16x16x32_bf16 v[24:27], v[144:147], v[226:229], v[24:27]
	v_mfma_f32_16x16x32_bf16 v[12:15], v[136:139], v[234:237], v[12:15]
	v_mfma_f32_16x16x32_bf16 v[8:11], v[144:147], v[234:237], v[8:11]
	v_mfma_f32_16x16x32_bf16 v[52:55], v[148:151], v[164:167], v[52:55]
	v_mfma_f32_16x16x32_bf16 v[48:51], v[156:159], v[164:167], v[48:51]
	v_mfma_f32_16x16x32_bf16 v[36:39], v[148:151], v[172:175], v[36:39]
	v_mfma_f32_16x16x32_bf16 v[32:35], v[156:159], v[172:175], v[32:35]
	v_mfma_f32_16x16x32_bf16 v[20:23], v[148:151], v[222:225], v[20:23]
	v_mfma_f32_16x16x32_bf16 v[16:19], v[156:159], v[222:225], v[16:19]
	v_mfma_f32_16x16x32_bf16 v[4:7], v[148:151], v[230:233], v[4:7]
	v_mfma_f32_16x16x32_bf16 v[0:3], v[156:159], v[230:233], v[0:3]
	v_mfma_f32_16x16x32_bf16 v[52:55], v[152:155], v[168:171], v[52:55]
	v_mfma_f32_16x16x32_bf16 v[48:51], v[160:163], v[168:171], v[48:51]
	v_mfma_f32_16x16x32_bf16 v[36:39], v[152:155], v[192:195], v[36:39]
	v_mfma_f32_16x16x32_bf16 v[32:35], v[160:163], v[192:195], v[32:35]
	v_mfma_f32_16x16x32_bf16 v[20:23], v[152:155], v[226:229], v[20:23]
	v_mfma_f32_16x16x32_bf16 v[16:19], v[160:163], v[226:229], v[16:19]
	v_mfma_f32_16x16x32_bf16 v[4:7], v[152:155], v[234:237], v[4:7]
	v_mfma_f32_16x16x32_bf16 v[0:3], v[160:163], v[234:237], v[0:3]
	s_setprio 0
	s_barrier
	s_add_i32 s65, 0, 0x18000
	s_add_i32 s68, 0, 0x1c000
	v_add_u32_e32 v144, s65, v198
	v_add_u32_e32 v160, s68, v198
	ds_read_b128 v[132:135], v144
	ds_read_b128 v[136:139], v144 offset:1024
	ds_read_b128 v[140:143], v144 offset:2048
	ds_read_b128 v[144:147], v144 offset:3072
	ds_read_b128 v[148:151], v160
	ds_read_b128 v[152:155], v160 offset:1024
	ds_read_b128 v[156:159], v160 offset:2048
	ds_read_b128 v[160:163], v160 offset:3072
	s_add_u32 s66, s66, 0x40000
	s_addc_u32 s67, s67, 0
	s_mov_b32 m0, s52
	v_lshl_add_u64 v[242:243], s[66:67], 0, v[176:177]
	ds_read_b128 v[164:167], v219 offset:32768
	ds_read_b128 v[168:171], v219 offset:33792
	ds_read_b128 v[172:175], v219 offset:34816
	ds_read_b128 v[192:195], v219 offset:35840
	ds_read_b128 v[222:225], v219 offset:36864
	ds_read_b128 v[226:229], v219 offset:37888
	ds_read_b128 v[230:233], v219 offset:38912
	ds_read_b128 v[234:237], v219 offset:39936
	global_load_lds_dwordx4 v[242:243], off
	v_lshl_add_u64 v[242:243], s[66:67], 0, v[180:181]
	s_mov_b32 m0, s53
	s_nop 0
	global_load_lds_dwordx4 v[242:243], off
	s_waitcnt vmcnt(8)
	s_waitcnt lgkmcnt(0)
	s_barrier
	s_setprio 1
	v_mfma_f32_16x16x32_bf16 v[124:127], v[132:135], v[164:167], v[124:127]
	v_mfma_f32_16x16x32_bf16 v[120:123], v[140:143], v[164:167], v[120:123]
	v_mfma_f32_16x16x32_bf16 v[108:111], v[132:135], v[172:175], v[108:111]
	v_mfma_f32_16x16x32_bf16 v[104:107], v[140:143], v[172:175], v[104:107]
	v_mfma_f32_16x16x32_bf16 v[92:95], v[132:135], v[222:225], v[92:95]
	v_mfma_f32_16x16x32_bf16 v[88:91], v[140:143], v[222:225], v[88:91]
	v_mfma_f32_16x16x32_bf16 v[76:79], v[132:135], v[230:233], v[76:79]
	v_mfma_f32_16x16x32_bf16 v[72:75], v[140:143], v[230:233], v[72:75]
	v_mfma_f32_16x16x32_bf16 v[124:127], v[136:139], v[168:171], v[124:127]
	v_mfma_f32_16x16x32_bf16 v[120:123], v[144:147], v[168:171], v[120:123]
	v_mfma_f32_16x16x32_bf16 v[108:111], v[136:139], v[192:195], v[108:111]
	v_mfma_f32_16x16x32_bf16 v[104:107], v[144:147], v[192:195], v[104:107]
	v_mfma_f32_16x16x32_bf16 v[92:95], v[136:139], v[226:229], v[92:95]
	v_mfma_f32_16x16x32_bf16 v[88:91], v[144:147], v[226:229], v[88:91]
	v_mfma_f32_16x16x32_bf16 v[76:79], v[136:139], v[234:237], v[76:79]
	v_mfma_f32_16x16x32_bf16 v[72:75], v[144:147], v[234:237], v[72:75]
	v_mfma_f32_16x16x32_bf16 v[116:119], v[148:151], v[164:167], v[116:119]
	v_mfma_f32_16x16x32_bf16 v[112:115], v[156:159], v[164:167], v[112:115]
	v_mfma_f32_16x16x32_bf16 v[100:103], v[148:151], v[172:175], v[100:103]
	v_mfma_f32_16x16x32_bf16 v[96:99], v[156:159], v[172:175], v[96:99]
	v_mfma_f32_16x16x32_bf16 v[84:87], v[148:151], v[222:225], v[84:87]
	v_mfma_f32_16x16x32_bf16 v[80:83], v[156:159], v[222:225], v[80:83]
	v_mfma_f32_16x16x32_bf16 v[68:71], v[148:151], v[230:233], v[68:71]
	v_mfma_f32_16x16x32_bf16 v[64:67], v[156:159], v[230:233], v[64:67]
	v_mfma_f32_16x16x32_bf16 v[116:119], v[152:155], v[168:171], v[116:119]
	v_mfma_f32_16x16x32_bf16 v[112:115], v[160:163], v[168:171], v[112:115]
	v_mfma_f32_16x16x32_bf16 v[100:103], v[152:155], v[192:195], v[100:103]
	v_mfma_f32_16x16x32_bf16 v[96:99], v[160:163], v[192:195], v[96:99]
	v_mfma_f32_16x16x32_bf16 v[84:87], v[152:155], v[226:229], v[84:87]
	v_mfma_f32_16x16x32_bf16 v[80:83], v[160:163], v[226:229], v[80:83]
	v_mfma_f32_16x16x32_bf16 v[68:71], v[152:155], v[234:237], v[68:71]
	v_mfma_f32_16x16x32_bf16 v[64:67], v[160:163], v[234:237], v[64:67]
	s_setprio 0
	s_barrier
	s_add_i32 s65, s65, s33
	v_lshl_add_u64 v[238:239], v[238:239], 0, s[24:25]
	s_mov_b32 m0, s65
	ds_read_b128 v[164:167], v219 offset:49152
	ds_read_b128 v[168:171], v219 offset:50176
	ds_read_b128 v[172:175], v219 offset:51200
	ds_read_b128 v[192:195], v219 offset:52224
	ds_read_b128 v[222:225], v219 offset:53248
	ds_read_b128 v[226:229], v219 offset:54272
	ds_read_b128 v[230:233], v219 offset:55296
	ds_read_b128 v[234:237], v219 offset:56320
	global_load_lds_dwordx4 v[238:239], off
	s_add_i32 m0, s65, 0x2000
	s_add_u32 s46, s46, 0x40080
	v_lshl_add_u64 v[238:239], v[240:241], 0, s[24:25]
	s_addc_u32 s47, s47, 0
	s_add_i32 s65, s68, s33
	global_load_lds_dwordx4 v[238:239], off
	v_lshl_add_u64 v[238:239], s[46:47], 0, v[178:179]
	s_mov_b32 m0, s65
	s_or_b32 s20, s20, 1
	global_load_lds_dwordx4 v[238:239], off
	v_lshl_add_u64 v[238:239], s[46:47], 0, v[182:183]
	s_add_i32 m0, s65, 0x2000
	s_lshl_b64 s[46:47], s[20:21], 7
	s_add_u32 s46, s49, s46
	s_addc_u32 s47, s48, s47
	global_load_lds_dwordx4 v[238:239], off
	v_lshl_add_u64 v[238:239], s[46:47], 0, v[176:177]
	s_mov_b32 m0, s56
	s_nop 0
	global_load_lds_dwordx4 v[238:239], off
	v_lshl_add_u64 v[238:239], s[46:47], 0, v[180:181]
	s_mov_b32 m0, s57
	s_nop 0
	global_load_lds_dwordx4 v[238:239], off
	s_waitcnt vmcnt(8)
	s_waitcnt lgkmcnt(0)
	s_barrier
	s_setprio 1
	v_mfma_f32_16x16x32_bf16 v[60:63], v[132:135], v[164:167], v[60:63]
	v_mfma_f32_16x16x32_bf16 v[56:59], v[140:143], v[164:167], v[56:59]
	v_mfma_f32_16x16x32_bf16 v[44:47], v[132:135], v[172:175], v[44:47]
	v_mfma_f32_16x16x32_bf16 v[40:43], v[140:143], v[172:175], v[40:43]
	v_mfma_f32_16x16x32_bf16 v[28:31], v[132:135], v[222:225], v[28:31]
	v_mfma_f32_16x16x32_bf16 v[24:27], v[140:143], v[222:225], v[24:27]
	v_mfma_f32_16x16x32_bf16 v[12:15], v[132:135], v[230:233], v[12:15]
	v_mfma_f32_16x16x32_bf16 v[8:11], v[140:143], v[230:233], v[8:11]
	v_mfma_f32_16x16x32_bf16 v[60:63], v[136:139], v[168:171], v[60:63]
	v_mfma_f32_16x16x32_bf16 v[56:59], v[144:147], v[168:171], v[56:59]
	v_mfma_f32_16x16x32_bf16 v[44:47], v[136:139], v[192:195], v[44:47]
	v_mfma_f32_16x16x32_bf16 v[40:43], v[144:147], v[192:195], v[40:43]
	v_mfma_f32_16x16x32_bf16 v[28:31], v[136:139], v[226:229], v[28:31]
	v_mfma_f32_16x16x32_bf16 v[24:27], v[144:147], v[226:229], v[24:27]
	v_mfma_f32_16x16x32_bf16 v[12:15], v[136:139], v[234:237], v[12:15]
	v_mfma_f32_16x16x32_bf16 v[8:11], v[144:147], v[234:237], v[8:11]
	v_mfma_f32_16x16x32_bf16 v[52:55], v[148:151], v[164:167], v[52:55]
	v_mfma_f32_16x16x32_bf16 v[48:51], v[156:159], v[164:167], v[48:51]
	v_mfma_f32_16x16x32_bf16 v[36:39], v[148:151], v[172:175], v[36:39]
	v_mfma_f32_16x16x32_bf16 v[32:35], v[156:159], v[172:175], v[32:35]
	v_mfma_f32_16x16x32_bf16 v[20:23], v[148:151], v[222:225], v[20:23]
	v_mfma_f32_16x16x32_bf16 v[16:19], v[156:159], v[222:225], v[16:19]
	v_mfma_f32_16x16x32_bf16 v[4:7], v[148:151], v[230:233], v[4:7]
	v_mfma_f32_16x16x32_bf16 v[0:3], v[156:159], v[230:233], v[0:3]
	v_mfma_f32_16x16x32_bf16 v[52:55], v[152:155], v[168:171], v[52:55]
	v_mfma_f32_16x16x32_bf16 v[48:51], v[160:163], v[168:171], v[48:51]
	v_mfma_f32_16x16x32_bf16 v[36:39], v[152:155], v[192:195], v[36:39]
	v_mfma_f32_16x16x32_bf16 v[32:35], v[160:163], v[192:195], v[32:35]
	v_mfma_f32_16x16x32_bf16 v[20:23], v[152:155], v[226:229], v[20:23]
	v_mfma_f32_16x16x32_bf16 v[16:19], v[160:163], v[226:229], v[16:19]
	v_mfma_f32_16x16x32_bf16 v[4:7], v[152:155], v[234:237], v[4:7]
	v_mfma_f32_16x16x32_bf16 v[0:3], v[160:163], v[234:237], v[0:3]
	s_setprio 0
	s_barrier
	s_add_u32 s44, s44, 0x100
	s_addc_u32 s45, s45, 0
	s_cmp_gt_u32 s63, 13
	s_mov_b32 s63, s64
	s_cbranch_scc0 .LBB0_504
	s_and_b64 vcc, exec, s[26:27]
	s_cbranch_vccz .LBB0_507
	s_barrier

.LBB0_599:
	s_add_u32 s16, s57, s38
	ds_read_b128 v[178:181], v173
	ds_read_b128 v[182:185], v173 offset:1024
	ds_read_b128 v[186:189], v173 offset:2048
	ds_read_b128 v[190:193], v173 offset:3072
	ds_read_b128 v[194:197], v174
	ds_read_b128 v[198:201], v174 offset:1024
	ds_read_b128 v[202:205], v174 offset:2048
	ds_read_b128 v[206:209], v174 offset:3072
	s_addc_u32 s42, s58, s39
	s_cmpk_eq_i32 s38, 0x700
	s_cselect_b64 s[40:41], -1, 0
	s_and_b64 s[40:41], s[40:41], exec
	s_cselect_b32 s41, s25, s42
	s_cselect_b32 s40, s27, s16
	s_add_i32 s60, s59, 2
	s_cmpk_eq_i32 s38, 0x700
	s_cselect_b64 s[42:43], -1, 0
	s_and_b64 s[62:63], s[42:43], exec
	s_cselect_b32 s16, 0, s60
	s_and_b64 s[42:43], s[42:43], s[4:5]
	s_and_b64 s[42:43], s[42:43], exec
	s_cselect_b32 s42, s29, s37
	s_cselect_b32 s43, s28, s36
	v_lshl_add_u64 v[214:215], v[144:145], 0, s[38:39]
	s_add_i32 m0, s35, 0xc000
	ds_read_b128 v[210:213], v175
	ds_read_b128 v[218:221], v175 offset:1024
	ds_read_b128 v[222:225], v175 offset:2048
	ds_read_b128 v[226:229], v175 offset:3072
	ds_read_b128 v[230:233], v175 offset:4096
	ds_read_b128 v[234:237], v175 offset:5120
	ds_read_b128 v[238:241], v175 offset:6144
	ds_read_b128 v[242:245], v175 offset:7168
	global_load_lds_dwordx4 v[214:215], off
	v_lshl_add_u64 v[214:215], v[146:147], 0, s[38:39]
	s_add_i32 m0, s35, 0xe000
	s_nop 0
	global_load_lds_dwordx4 v[214:215], off
	s_waitcnt vmcnt(8)
	s_waitcnt lgkmcnt(0)
	s_barrier
	s_setprio 1
	v_mfma_f32_16x16x32_bf16 v[124:127], v[178:181], v[210:213], v[124:127]
	v_mfma_f32_16x16x32_bf16 v[120:123], v[186:189], v[210:213], v[120:123]
	v_mfma_f32_16x16x32_bf16 v[116:119], v[178:181], v[222:225], v[116:119]
	v_mfma_f32_16x16x32_bf16 v[108:111], v[186:189], v[222:225], v[108:111]
	v_mfma_f32_16x16x32_bf16 v[100:103], v[178:181], v[230:233], v[100:103]
	v_mfma_f32_16x16x32_bf16 v[92:95], v[186:189], v[230:233], v[92:95]
	v_mfma_f32_16x16x32_bf16 v[84:87], v[178:181], v[238:241], v[84:87]
	v_mfma_f32_16x16x32_bf16 v[76:79], v[186:189], v[238:241], v[76:79]
	v_mfma_f32_16x16x32_bf16 v[124:127], v[182:185], v[218:221], v[124:127]
	v_mfma_f32_16x16x32_bf16 v[120:123], v[190:193], v[218:221], v[120:123]
	v_mfma_f32_16x16x32_bf16 v[116:119], v[182:185], v[226:229], v[116:119]
	v_mfma_f32_16x16x32_bf16 v[108:111], v[190:193], v[226:229], v[108:111]
	v_mfma_f32_16x16x32_bf16 v[100:103], v[182:185], v[234:237], v[100:103]
	v_mfma_f32_16x16x32_bf16 v[92:95], v[190:193], v[234:237], v[92:95]
	v_mfma_f32_16x16x32_bf16 v[84:87], v[182:185], v[242:245], v[84:87]
	v_mfma_f32_16x16x32_bf16 v[76:79], v[190:193], v[242:245], v[76:79]
	v_mfma_f32_16x16x32_bf16 v[112:115], v[194:197], v[210:213], v[112:115]
	v_mfma_f32_16x16x32_bf16 v[104:107], v[202:205], v[210:213], v[104:107]
	v_mfma_f32_16x16x32_bf16 v[96:99], v[194:197], v[222:225], v[96:99]
	v_mfma_f32_16x16x32_bf16 v[88:91], v[202:205], v[222:225], v[88:91]
	v_mfma_f32_16x16x32_bf16 v[80:83], v[194:197], v[230:233], v[80:83]
	v_mfma_f32_16x16x32_bf16 v[72:75], v[202:205], v[230:233], v[72:75]
	v_mfma_f32_16x16x32_bf16 v[68:71], v[194:197], v[238:241], v[68:71]
	v_mfma_f32_16x16x32_bf16 v[64:67], v[202:205], v[238:241], v[64:67]
	v_mfma_f32_16x16x32_bf16 v[112:115], v[198:201], v[218:221], v[112:115]
	v_mfma_f32_16x16x32_bf16 v[104:107], v[206:209], v[218:221], v[104:107]
	v_mfma_f32_16x16x32_bf16 v[96:99], v[198:201], v[226:229], v[96:99]
	v_mfma_f32_16x16x32_bf16 v[88:91], v[206:209], v[226:229], v[88:91]
	v_mfma_f32_16x16x32_bf16 v[80:83], v[198:201], v[234:237], v[80:83]
	v_mfma_f32_16x16x32_bf16 v[72:75], v[206:209], v[234:237], v[72:75]
	v_mfma_f32_16x16x32_bf16 v[68:71], v[198:201], v[242:245], v[68:71]
	v_mfma_f32_16x16x32_bf16 v[64:67], v[206:209], v[242:245], v[64:67]
	s_setprio 0
	s_barrier
	s_add_i32 s61, s51, s33
	v_lshl_add_u64 v[214:215], s[40:41], 0, v[130:131]
	s_mov_b32 m0, s61
	ds_read_b128 v[210:213], v175 offset:16384
	ds_read_b128 v[218:221], v175 offset:17408
	ds_read_b128 v[222:225], v175 offset:18432
	ds_read_b128 v[226:229], v175 offset:19456
	ds_read_b128 v[230:233], v175 offset:20480
	ds_read_b128 v[234:237], v175 offset:21504
	ds_read_b128 v[238:241], v175 offset:22528
	ds_read_b128 v[242:245], v175 offset:23552
	global_load_lds_dwordx4 v[214:215], off
	s_add_i32 m0, s61, 0x2000
	s_add_u32 s62, s40, 0x40000
	v_lshl_add_u64 v[246:247], s[40:41], 0, v[134:135]
	s_addc_u32 s63, s41, 0
	s_add_i32 s61, s52, s33
	global_load_lds_dwordx4 v[246:247], off
	v_lshl_add_u64 v[248:249], s[62:63], 0, v[130:131]
	s_mov_b32 m0, s61
	s_nop 0
	global_load_lds_dwordx4 v[248:249], off
	v_lshl_add_u64 v[248:249], s[62:63], 0, v[134:135]
	s_add_i32 m0, s61, 0x2000
	s_lshl_b64 s[62:63], s[16:17], 7
	s_add_u32 s62, s43, s62
	s_addc_u32 s63, s42, s63
	global_load_lds_dwordx4 v[248:249], off
	v_lshl_add_u64 v[248:249], s[62:63], 0, v[128:129]
	s_mov_b32 m0, s35
	s_nop 0
	global_load_lds_dwordx4 v[248:249], off
	v_lshl_add_u64 v[248:249], s[62:63], 0, v[132:133]
	s_mov_b32 m0, s45
	s_nop 0
	global_load_lds_dwordx4 v[248:249], off
	s_waitcnt vmcnt(8)
	s_waitcnt lgkmcnt(0)
	s_barrier
	s_setprio 1
	v_mfma_f32_16x16x32_bf16 v[60:63], v[178:181], v[210:213], v[60:63]
	v_mfma_f32_16x16x32_bf16 v[56:59], v[186:189], v[210:213], v[56:59]
	v_mfma_f32_16x16x32_bf16 v[52:55], v[178:181], v[222:225], v[52:55]
	v_mfma_f32_16x16x32_bf16 v[44:47], v[186:189], v[222:225], v[44:47]
	v_mfma_f32_16x16x32_bf16 v[36:39], v[178:181], v[230:233], v[36:39]
	v_mfma_f32_16x16x32_bf16 v[28:31], v[186:189], v[230:233], v[28:31]
	v_mfma_f32_16x16x32_bf16 v[16:19], v[178:181], v[238:241], v[16:19]
	v_mfma_f32_16x16x32_bf16 v[8:11], v[186:189], v[238:241], v[8:11]
	v_mfma_f32_16x16x32_bf16 v[60:63], v[182:185], v[218:221], v[60:63]
	v_mfma_f32_16x16x32_bf16 v[56:59], v[190:193], v[218:221], v[56:59]
	v_mfma_f32_16x16x32_bf16 v[52:55], v[182:185], v[226:229], v[52:55]
	v_mfma_f32_16x16x32_bf16 v[44:47], v[190:193], v[226:229], v[44:47]
	v_mfma_f32_16x16x32_bf16 v[36:39], v[182:185], v[234:237], v[36:39]
	v_mfma_f32_16x16x32_bf16 v[28:31], v[190:193], v[234:237], v[28:31]
	v_mfma_f32_16x16x32_bf16 v[16:19], v[182:185], v[242:245], v[16:19]
	v_mfma_f32_16x16x32_bf16 v[8:11], v[190:193], v[242:245], v[8:11]
	v_mfma_f32_16x16x32_bf16 v[48:51], v[194:197], v[210:213], v[48:51]
	v_mfma_f32_16x16x32_bf16 v[40:43], v[202:205], v[210:213], v[40:43]
	v_mfma_f32_16x16x32_bf16 v[32:35], v[194:197], v[222:225], v[32:35]
	v_mfma_f32_16x16x32_bf16 v[24:27], v[202:205], v[222:225], v[24:27]
	v_mfma_f32_16x16x32_bf16 v[20:23], v[194:197], v[230:233], v[20:23]
	v_mfma_f32_16x16x32_bf16 v[12:15], v[202:205], v[230:233], v[12:15]
	v_mfma_f32_16x16x32_bf16 v[4:7], v[194:197], v[238:241], v[4:7]
	v_mfma_f32_16x16x32_bf16 v[0:3], v[202:205], v[238:241], v[0:3]
	v_mfma_f32_16x16x32_bf16 v[48:51], v[198:201], v[218:221], v[48:51]
	v_mfma_f32_16x16x32_bf16 v[40:43], v[206:209], v[218:221], v[40:43]
	v_mfma_f32_16x16x32_bf16 v[32:35], v[198:201], v[226:229], v[32:35]
	v_mfma_f32_16x16x32_bf16 v[24:27], v[206:209], v[226:229], v[24:27]
	v_mfma_f32_16x16x32_bf16 v[20:23], v[198:201], v[234:237], v[20:23]
	v_mfma_f32_16x16x32_bf16 v[12:15], v[206:209], v[234:237], v[12:15]
	v_mfma_f32_16x16x32_bf16 v[4:7], v[198:201], v[242:245], v[4:7]
	v_mfma_f32_16x16x32_bf16 v[0:3], v[206:209], v[242:245], v[0:3]
	s_setprio 0
	s_barrier
	s_add_i32 s61, 0, 0x18000
	v_add_u32_e32 v148, s61, v151
	s_add_i32 s64, 0, 0x1c000
	ds_read_b128 v[178:181], v148
	ds_read_b128 v[182:185], v148 offset:1024
	ds_read_b128 v[186:189], v148 offset:2048
	ds_read_b128 v[190:193], v148 offset:3072
	v_add_u32_e32 v148, s64, v151
	ds_read_b128 v[194:197], v148
	ds_read_b128 v[198:201], v148 offset:1024
	ds_read_b128 v[202:205], v148 offset:2048
	ds_read_b128 v[206:209], v148 offset:3072
	s_add_u32 s62, s62, 0x40000
	s_addc_u32 s63, s63, 0
	s_mov_b32 m0, s46
	v_lshl_add_u64 v[248:249], s[62:63], 0, v[128:129]
	ds_read_b128 v[210:213], v175 offset:32768
	ds_read_b128 v[218:221], v175 offset:33792
	ds_read_b128 v[222:225], v175 offset:34816
	ds_read_b128 v[226:229], v175 offset:35840
	ds_read_b128 v[230:233], v175 offset:36864
	ds_read_b128 v[234:237], v175 offset:37888
	ds_read_b128 v[238:241], v175 offset:38912
	ds_read_b128 v[242:245], v175 offset:39936
	global_load_lds_dwordx4 v[248:249], off
	v_lshl_add_u64 v[248:249], s[62:63], 0, v[132:133]
	s_mov_b32 m0, s47
	s_nop 0
	global_load_lds_dwordx4 v[248:249], off
	s_waitcnt vmcnt(8)
	s_waitcnt lgkmcnt(0)
	s_barrier
	s_setprio 1
	v_mfma_f32_16x16x32_bf16 v[124:127], v[178:181], v[210:213], v[124:127]
	v_mfma_f32_16x16x32_bf16 v[120:123], v[186:189], v[210:213], v[120:123]
	v_mfma_f32_16x16x32_bf16 v[116:119], v[178:181], v[222:225], v[116:119]
	v_mfma_f32_16x16x32_bf16 v[108:111], v[186:189], v[222:225], v[108:111]
	v_mfma_f32_16x16x32_bf16 v[100:103], v[178:181], v[230:233], v[100:103]
	v_mfma_f32_16x16x32_bf16 v[92:95], v[186:189], v[230:233], v[92:95]
	v_mfma_f32_16x16x32_bf16 v[84:87], v[178:181], v[238:241], v[84:87]
	v_mfma_f32_16x16x32_bf16 v[76:79], v[186:189], v[238:241], v[76:79]
	v_mfma_f32_16x16x32_bf16 v[124:127], v[182:185], v[218:221], v[124:127]
	v_mfma_f32_16x16x32_bf16 v[120:123], v[190:193], v[218:221], v[120:123]
	v_mfma_f32_16x16x32_bf16 v[116:119], v[182:185], v[226:229], v[116:119]
	v_mfma_f32_16x16x32_bf16 v[108:111], v[190:193], v[226:229], v[108:111]
	v_mfma_f32_16x16x32_bf16 v[100:103], v[182:185], v[234:237], v[100:103]
	v_mfma_f32_16x16x32_bf16 v[92:95], v[190:193], v[234:237], v[92:95]
	v_mfma_f32_16x16x32_bf16 v[84:87], v[182:185], v[242:245], v[84:87]
	v_mfma_f32_16x16x32_bf16 v[76:79], v[190:193], v[242:245], v[76:79]
	v_mfma_f32_16x16x32_bf16 v[112:115], v[194:197], v[210:213], v[112:115]
	v_mfma_f32_16x16x32_bf16 v[104:107], v[202:205], v[210:213], v[104:107]
	v_mfma_f32_16x16x32_bf16 v[96:99], v[194:197], v[222:225], v[96:99]
	v_mfma_f32_16x16x32_bf16 v[88:91], v[202:205], v[222:225], v[88:91]
	v_mfma_f32_16x16x32_bf16 v[80:83], v[194:197], v[230:233], v[80:83]
	v_mfma_f32_16x16x32_bf16 v[72:75], v[202:205], v[230:233], v[72:75]
	v_mfma_f32_16x16x32_bf16 v[68:71], v[194:197], v[238:241], v[68:71]
	v_mfma_f32_16x16x32_bf16 v[64:67], v[202:205], v[238:241], v[64:67]
	v_mfma_f32_16x16x32_bf16 v[112:115], v[198:201], v[218:221], v[112:115]
	v_mfma_f32_16x16x32_bf16 v[104:107], v[206:209], v[218:221], v[104:107]
	v_mfma_f32_16x16x32_bf16 v[96:99], v[198:201], v[226:229], v[96:99]
	v_mfma_f32_16x16x32_bf16 v[88:91], v[206:209], v[226:229], v[88:91]
	v_mfma_f32_16x16x32_bf16 v[80:83], v[198:201], v[234:237], v[80:83]
	v_mfma_f32_16x16x32_bf16 v[72:75], v[206:209], v[234:237], v[72:75]
	v_mfma_f32_16x16x32_bf16 v[68:71], v[198:201], v[242:245], v[68:71]
	v_mfma_f32_16x16x32_bf16 v[64:67], v[206:209], v[242:245], v[64:67]
	s_setprio 0
	s_barrier
	s_add_i32 s61, s61, s33
	v_lshl_add_u64 v[214:215], v[214:215], 0, s[20:21]
	s_mov_b32 m0, s61
	ds_read_b128 v[210:213], v175 offset:49152
	ds_read_b128 v[218:221], v175 offset:50176
	ds_read_b128 v[222:225], v175 offset:51200
	ds_read_b128 v[226:229], v175 offset:52224
	ds_read_b128 v[230:233], v175 offset:53248
	ds_read_b128 v[234:237], v175 offset:54272
	ds_read_b128 v[238:241], v175 offset:55296
	ds_read_b128 v[242:245], v175 offset:56320
	global_load_lds_dwordx4 v[214:215], off
	s_add_i32 m0, s61, 0x2000
	s_add_u32 s40, s40, 0x40080
	v_lshl_add_u64 v[214:215], v[246:247], 0, s[20:21]
	s_addc_u32 s41, s41, 0
	s_add_i32 s61, s64, s33
	global_load_lds_dwordx4 v[214:215], off
	v_lshl_add_u64 v[214:215], s[40:41], 0, v[130:131]
	s_mov_b32 m0, s61
	s_or_b32 s16, s16, 1
	global_load_lds_dwordx4 v[214:215], off
	v_lshl_add_u64 v[214:215], s[40:41], 0, v[134:135]
	s_add_i32 m0, s61, 0x2000
	s_lshl_b64 s[40:41], s[16:17], 7
	s_add_u32 s40, s43, s40
	s_addc_u32 s41, s42, s41
	global_load_lds_dwordx4 v[214:215], off
	v_lshl_add_u64 v[214:215], s[40:41], 0, v[128:129]
	s_mov_b32 m0, s49
	s_nop 0
	global_load_lds_dwordx4 v[214:215], off
	v_lshl_add_u64 v[214:215], s[40:41], 0, v[132:133]
	s_mov_b32 m0, s50
	s_nop 0
	global_load_lds_dwordx4 v[214:215], off
	s_waitcnt vmcnt(8)
	s_waitcnt lgkmcnt(0)
	s_barrier
	s_setprio 1
	v_mfma_f32_16x16x32_bf16 v[60:63], v[178:181], v[210:213], v[60:63]
	v_mfma_f32_16x16x32_bf16 v[56:59], v[186:189], v[210:213], v[56:59]
	v_mfma_f32_16x16x32_bf16 v[52:55], v[178:181], v[222:225], v[52:55]
	v_mfma_f32_16x16x32_bf16 v[44:47], v[186:189], v[222:225], v[44:47]
	v_mfma_f32_16x16x32_bf16 v[36:39], v[178:181], v[230:233], v[36:39]
	v_mfma_f32_16x16x32_bf16 v[28:31], v[186:189], v[230:233], v[28:31]
	v_mfma_f32_16x16x32_bf16 v[16:19], v[178:181], v[238:241], v[16:19]
	v_mfma_f32_16x16x32_bf16 v[8:11], v[186:189], v[238:241], v[8:11]
	v_mfma_f32_16x16x32_bf16 v[60:63], v[182:185], v[218:221], v[60:63]
	v_mfma_f32_16x16x32_bf16 v[56:59], v[190:193], v[218:221], v[56:59]
	v_mfma_f32_16x16x32_bf16 v[52:55], v[182:185], v[226:229], v[52:55]
	v_mfma_f32_16x16x32_bf16 v[44:47], v[190:193], v[226:229], v[44:47]
	v_mfma_f32_16x16x32_bf16 v[36:39], v[182:185], v[234:237], v[36:39]
	v_mfma_f32_16x16x32_bf16 v[28:31], v[190:193], v[234:237], v[28:31]
	v_mfma_f32_16x16x32_bf16 v[16:19], v[182:185], v[242:245], v[16:19]
	v_mfma_f32_16x16x32_bf16 v[8:11], v[190:193], v[242:245], v[8:11]
	v_mfma_f32_16x16x32_bf16 v[48:51], v[194:197], v[210:213], v[48:51]
	v_mfma_f32_16x16x32_bf16 v[40:43], v[202:205], v[210:213], v[40:43]
	v_mfma_f32_16x16x32_bf16 v[32:35], v[194:197], v[222:225], v[32:35]
	v_mfma_f32_16x16x32_bf16 v[24:27], v[202:205], v[222:225], v[24:27]
	v_mfma_f32_16x16x32_bf16 v[20:23], v[194:197], v[230:233], v[20:23]
	v_mfma_f32_16x16x32_bf16 v[12:15], v[202:205], v[230:233], v[12:15]
	v_mfma_f32_16x16x32_bf16 v[4:7], v[194:197], v[238:241], v[4:7]
	v_mfma_f32_16x16x32_bf16 v[0:3], v[202:205], v[238:241], v[0:3]
	v_mfma_f32_16x16x32_bf16 v[48:51], v[198:201], v[218:221], v[48:51]
	v_mfma_f32_16x16x32_bf16 v[40:43], v[206:209], v[218:221], v[40:43]
	v_mfma_f32_16x16x32_bf16 v[32:35], v[198:201], v[226:229], v[32:35]
	v_mfma_f32_16x16x32_bf16 v[24:27], v[206:209], v[226:229], v[24:27]
	v_mfma_f32_16x16x32_bf16 v[20:23], v[198:201], v[234:237], v[20:23]
	v_mfma_f32_16x16x32_bf16 v[12:15], v[206:209], v[234:237], v[12:15]
	v_mfma_f32_16x16x32_bf16 v[4:7], v[198:201], v[242:245], v[4:7]
	v_mfma_f32_16x16x32_bf16 v[0:3], v[206:209], v[242:245], v[0:3]
	s_setprio 0
	s_barrier
	s_add_u32 s38, s38, 0x100
	s_addc_u32 s39, s39, 0
	s_cmp_gt_u32 s59, 13
	s_mov_b32 s59, s60
	s_cbranch_scc0 .LBB0_599
	s_and_b64 vcc, exec, s[22:23]
	s_cbranch_vccz .LBB0_602
	s_barrier

.LBB0_678:
	ds_read_b128 v[144:147], v193
	ds_read_b128 v[148:151], v193 offset:1024
	ds_read_b128 v[152:155], v193 offset:2048
	ds_read_b128 v[156:159], v193 offset:3072
	ds_read_b128 v[160:163], v194
	ds_read_b128 v[164:167], v194 offset:1024
	ds_read_b128 v[168:171], v194 offset:2048
	ds_read_b128 v[172:175], v194 offset:3072
	s_cmp_eq_u32 s22, 0x7e04000
	s_cselect_b64 s[24:25], -1, 0
	s_and_b64 s[24:25], s[24:25], exec
	s_cselect_b32 s25, s9, s43
	s_cselect_b32 s24, s11, s42
	s_add_i32 s45, s44, 2
	s_cmp_eq_u32 s22, 0x7e04000
	s_cselect_b64 s[26:27], -1, 0
	s_and_b64 s[46:47], s[26:27], exec
	s_cselect_b32 s6, 0, s45
	s_and_b64 s[26:27], s[26:27], s[4:5]
	s_and_b64 s[26:27], s[26:27], exec
	s_cselect_b32 s26, s15, s21
	s_cselect_b32 s27, s14, s20
	v_lshl_add_u64 v[188:189], v[140:141], 0, s[22:23]
	s_add_i32 m0, s19, 0xc000
	ds_read_b128 v[176:179], v195
	ds_read_b128 v[180:183], v195 offset:1024
	ds_read_b128 v[184:187], v195 offset:2048
	ds_read_b128 v[196:199], v195 offset:3072
	ds_read_b128 v[200:203], v195 offset:4096
	ds_read_b128 v[204:207], v195 offset:5120
	ds_read_b128 v[208:211], v195 offset:6144
	ds_read_b128 v[212:215], v195 offset:7168
	global_load_lds_dwordx4 v[188:189], off
	v_lshl_add_u64 v[188:189], v[142:143], 0, s[22:23]
	s_add_i32 m0, s19, 0xe000
	s_nop 0
	global_load_lds_dwordx4 v[188:189], off
	s_waitcnt vmcnt(8)
	s_waitcnt lgkmcnt(0)
	s_barrier
	s_setprio 1
	v_mfma_f32_16x16x32_bf16 v[124:127], v[144:147], v[176:179], v[124:127]
	v_mfma_f32_16x16x32_bf16 v[120:123], v[152:155], v[176:179], v[120:123]
	v_mfma_f32_16x16x32_bf16 v[112:115], v[144:147], v[184:187], v[112:115]
	v_mfma_f32_16x16x32_bf16 v[104:107], v[152:155], v[184:187], v[104:107]
	v_mfma_f32_16x16x32_bf16 v[96:99], v[144:147], v[200:203], v[96:99]
	v_mfma_f32_16x16x32_bf16 v[88:91], v[152:155], v[200:203], v[88:91]
	v_mfma_f32_16x16x32_bf16 v[80:83], v[144:147], v[208:211], v[80:83]
	v_mfma_f32_16x16x32_bf16 v[72:75], v[152:155], v[208:211], v[72:75]
	v_mfma_f32_16x16x32_bf16 v[124:127], v[148:151], v[180:183], v[124:127]
	v_mfma_f32_16x16x32_bf16 v[120:123], v[156:159], v[180:183], v[120:123]
	v_mfma_f32_16x16x32_bf16 v[112:115], v[148:151], v[196:199], v[112:115]
	v_mfma_f32_16x16x32_bf16 v[104:107], v[156:159], v[196:199], v[104:107]
	v_mfma_f32_16x16x32_bf16 v[96:99], v[148:151], v[204:207], v[96:99]
	v_mfma_f32_16x16x32_bf16 v[88:91], v[156:159], v[204:207], v[88:91]
	v_mfma_f32_16x16x32_bf16 v[80:83], v[148:151], v[212:215], v[80:83]
	v_mfma_f32_16x16x32_bf16 v[72:75], v[156:159], v[212:215], v[72:75]
	v_mfma_f32_16x16x32_bf16 v[116:119], v[160:163], v[176:179], v[116:119]
	v_mfma_f32_16x16x32_bf16 v[108:111], v[168:171], v[176:179], v[108:111]
	v_mfma_f32_16x16x32_bf16 v[100:103], v[160:163], v[184:187], v[100:103]
	v_mfma_f32_16x16x32_bf16 v[92:95], v[168:171], v[184:187], v[92:95]
	v_mfma_f32_16x16x32_bf16 v[84:87], v[160:163], v[200:203], v[84:87]
	v_mfma_f32_16x16x32_bf16 v[76:79], v[168:171], v[200:203], v[76:79]
	v_mfma_f32_16x16x32_bf16 v[68:71], v[160:163], v[208:211], v[68:71]
	v_mfma_f32_16x16x32_bf16 v[64:67], v[168:171], v[208:211], v[64:67]
	v_mfma_f32_16x16x32_bf16 v[116:119], v[164:167], v[180:183], v[116:119]
	v_mfma_f32_16x16x32_bf16 v[108:111], v[172:175], v[180:183], v[108:111]
	v_mfma_f32_16x16x32_bf16 v[100:103], v[164:167], v[196:199], v[100:103]
	v_mfma_f32_16x16x32_bf16 v[92:95], v[172:175], v[196:199], v[92:95]
	v_mfma_f32_16x16x32_bf16 v[84:87], v[164:167], v[204:207], v[84:87]
	v_mfma_f32_16x16x32_bf16 v[76:79], v[172:175], v[204:207], v[76:79]
	v_mfma_f32_16x16x32_bf16 v[68:71], v[164:167], v[212:215], v[68:71]
	v_mfma_f32_16x16x32_bf16 v[64:67], v[172:175], v[212:215], v[64:67]
	s_setprio 0
	s_barrier
	s_add_i32 s46, s38, s29
	v_lshl_add_u64 v[188:189], s[24:25], 0, v[128:129]
	s_mov_b32 m0, s46
	ds_read_b128 v[176:179], v195 offset:16384
	ds_read_b128 v[180:183], v195 offset:17408
	ds_read_b128 v[184:187], v195 offset:18432
	ds_read_b128 v[196:199], v195 offset:19456
	ds_read_b128 v[200:203], v195 offset:20480
	ds_read_b128 v[204:207], v195 offset:21504
	ds_read_b128 v[208:211], v195 offset:22528
	ds_read_b128 v[212:215], v195 offset:23552
	global_load_lds_dwordx4 v[188:189], off
	s_add_i32 m0, s46, 0x2000
	s_add_u32 s46, s24, 0x4000
	v_lshl_add_u64 v[188:189], s[24:25], 0, v[130:131]
	s_addc_u32 s47, s25, 0
	s_add_i32 s48, s39, s29
	global_load_lds_dwordx4 v[188:189], off
	v_lshl_add_u64 v[188:189], s[46:47], 0, v[128:129]
	s_mov_b32 m0, s48
	s_nop 0
	global_load_lds_dwordx4 v[188:189], off
	v_lshl_add_u64 v[188:189], s[46:47], 0, v[130:131]
	s_add_i32 m0, s48, 0x2000
	s_lshl_b64 s[46:47], s[6:7], 21
	s_add_u32 s46, s27, s46
	s_addc_u32 s47, s26, s47
	global_load_lds_dwordx4 v[188:189], off
	v_lshl_add_u64 v[188:189], s[46:47], 0, v[128:129]
	s_mov_b32 m0, s19
	s_nop 0
	global_load_lds_dwordx4 v[188:189], off
	v_lshl_add_u64 v[188:189], s[46:47], 0, v[130:131]
	s_mov_b32 m0, s31
	s_nop 0
	global_load_lds_dwordx4 v[188:189], off
	s_waitcnt vmcnt(8)
	s_waitcnt lgkmcnt(0)
	s_barrier
	s_setprio 1
	v_mfma_f32_16x16x32_bf16 v[60:63], v[144:147], v[176:179], v[60:63]
	v_mfma_f32_16x16x32_bf16 v[56:59], v[152:155], v[176:179], v[56:59]
	v_mfma_f32_16x16x32_bf16 v[48:51], v[144:147], v[184:187], v[48:51]
	v_mfma_f32_16x16x32_bf16 v[40:43], v[152:155], v[184:187], v[40:43]
	v_mfma_f32_16x16x32_bf16 v[32:35], v[144:147], v[200:203], v[32:35]
	v_mfma_f32_16x16x32_bf16 v[24:27], v[152:155], v[200:203], v[24:27]
	v_mfma_f32_16x16x32_bf16 v[16:19], v[144:147], v[208:211], v[16:19]
	v_mfma_f32_16x16x32_bf16 v[8:11], v[152:155], v[208:211], v[8:11]
	v_mfma_f32_16x16x32_bf16 v[60:63], v[148:151], v[180:183], v[60:63]
	v_mfma_f32_16x16x32_bf16 v[56:59], v[156:159], v[180:183], v[56:59]
	v_mfma_f32_16x16x32_bf16 v[48:51], v[148:151], v[196:199], v[48:51]
	v_mfma_f32_16x16x32_bf16 v[40:43], v[156:159], v[196:199], v[40:43]
	v_mfma_f32_16x16x32_bf16 v[32:35], v[148:151], v[204:207], v[32:35]
	v_mfma_f32_16x16x32_bf16 v[24:27], v[156:159], v[204:207], v[24:27]
	v_mfma_f32_16x16x32_bf16 v[16:19], v[148:151], v[212:215], v[16:19]
	v_mfma_f32_16x16x32_bf16 v[8:11], v[156:159], v[212:215], v[8:11]
	v_mfma_f32_16x16x32_bf16 v[52:55], v[160:163], v[176:179], v[52:55]
	v_mfma_f32_16x16x32_bf16 v[44:47], v[168:171], v[176:179], v[44:47]
	v_mfma_f32_16x16x32_bf16 v[36:39], v[160:163], v[184:187], v[36:39]
	v_mfma_f32_16x16x32_bf16 v[28:31], v[168:171], v[184:187], v[28:31]
	v_mfma_f32_16x16x32_bf16 v[20:23], v[160:163], v[200:203], v[20:23]
	v_mfma_f32_16x16x32_bf16 v[12:15], v[168:171], v[200:203], v[12:15]
	v_mfma_f32_16x16x32_bf16 v[4:7], v[160:163], v[208:211], v[4:7]
	v_mfma_f32_16x16x32_bf16 v[0:3], v[168:171], v[208:211], v[0:3]
	v_mfma_f32_16x16x32_bf16 v[52:55], v[164:167], v[180:183], v[52:55]
	v_mfma_f32_16x16x32_bf16 v[44:47], v[172:175], v[180:183], v[44:47]
	v_mfma_f32_16x16x32_bf16 v[36:39], v[164:167], v[196:199], v[36:39]
	v_mfma_f32_16x16x32_bf16 v[28:31], v[172:175], v[196:199], v[28:31]
	v_mfma_f32_16x16x32_bf16 v[20:23], v[164:167], v[204:207], v[20:23]
	v_mfma_f32_16x16x32_bf16 v[12:15], v[172:175], v[204:207], v[12:15]
	v_mfma_f32_16x16x32_bf16 v[4:7], v[164:167], v[212:215], v[4:7]
	v_mfma_f32_16x16x32_bf16 v[0:3], v[172:175], v[212:215], v[0:3]
	s_setprio 0
	s_barrier
	s_add_i32 s48, 0, 0x18000
	s_add_i32 s49, 0, 0x1c000
	v_add_u32_e32 v156, s48, v191
	v_add_u32_e32 v172, s49, v191
	ds_read_b128 v[144:147], v156
	ds_read_b128 v[148:151], v156 offset:1024
	ds_read_b128 v[152:155], v156 offset:2048
	ds_read_b128 v[156:159], v156 offset:3072
	ds_read_b128 v[160:163], v172
	ds_read_b128 v[164:167], v172 offset:1024
	ds_read_b128 v[168:171], v172 offset:2048
	ds_read_b128 v[172:175], v172 offset:3072
	s_add_u32 s46, s46, 0x4000
	s_addc_u32 s47, s47, 0
	s_mov_b32 m0, s33
	v_lshl_add_u64 v[188:189], s[46:47], 0, v[128:129]
	ds_read_b128 v[176:179], v195 offset:32768
	ds_read_b128 v[180:183], v195 offset:33792
	ds_read_b128 v[184:187], v195 offset:34816
	ds_read_b128 v[196:199], v195 offset:35840
	ds_read_b128 v[200:203], v195 offset:36864
	ds_read_b128 v[204:207], v195 offset:37888
	ds_read_b128 v[208:211], v195 offset:38912
	ds_read_b128 v[212:215], v195 offset:39936
	global_load_lds_dwordx4 v[188:189], off
	v_lshl_add_u64 v[188:189], s[46:47], 0, v[130:131]
	s_mov_b32 m0, s34
	s_nop 0
	global_load_lds_dwordx4 v[188:189], off
	s_waitcnt vmcnt(8)
	s_waitcnt lgkmcnt(0)
	s_barrier
	s_setprio 1
	v_mfma_f32_16x16x32_bf16 v[124:127], v[144:147], v[176:179], v[124:127]
	v_mfma_f32_16x16x32_bf16 v[120:123], v[152:155], v[176:179], v[120:123]
	v_mfma_f32_16x16x32_bf16 v[112:115], v[144:147], v[184:187], v[112:115]
	v_mfma_f32_16x16x32_bf16 v[104:107], v[152:155], v[184:187], v[104:107]
	v_mfma_f32_16x16x32_bf16 v[96:99], v[144:147], v[200:203], v[96:99]
	v_mfma_f32_16x16x32_bf16 v[88:91], v[152:155], v[200:203], v[88:91]
	v_mfma_f32_16x16x32_bf16 v[80:83], v[144:147], v[208:211], v[80:83]
	v_mfma_f32_16x16x32_bf16 v[72:75], v[152:155], v[208:211], v[72:75]
	v_mfma_f32_16x16x32_bf16 v[124:127], v[148:151], v[180:183], v[124:127]
	v_mfma_f32_16x16x32_bf16 v[120:123], v[156:159], v[180:183], v[120:123]
	v_mfma_f32_16x16x32_bf16 v[112:115], v[148:151], v[196:199], v[112:115]
	v_mfma_f32_16x16x32_bf16 v[104:107], v[156:159], v[196:199], v[104:107]
	v_mfma_f32_16x16x32_bf16 v[96:99], v[148:151], v[204:207], v[96:99]
	v_mfma_f32_16x16x32_bf16 v[88:91], v[156:159], v[204:207], v[88:91]
	v_mfma_f32_16x16x32_bf16 v[80:83], v[148:151], v[212:215], v[80:83]
	v_mfma_f32_16x16x32_bf16 v[72:75], v[156:159], v[212:215], v[72:75]
	v_mfma_f32_16x16x32_bf16 v[116:119], v[160:163], v[176:179], v[116:119]
	v_mfma_f32_16x16x32_bf16 v[108:111], v[168:171], v[176:179], v[108:111]
	v_mfma_f32_16x16x32_bf16 v[100:103], v[160:163], v[184:187], v[100:103]
	v_mfma_f32_16x16x32_bf16 v[92:95], v[168:171], v[184:187], v[92:95]
	v_mfma_f32_16x16x32_bf16 v[84:87], v[160:163], v[200:203], v[84:87]
	v_mfma_f32_16x16x32_bf16 v[76:79], v[168:171], v[200:203], v[76:79]
	v_mfma_f32_16x16x32_bf16 v[68:71], v[160:163], v[208:211], v[68:71]
	v_mfma_f32_16x16x32_bf16 v[64:67], v[168:171], v[208:211], v[64:67]
	v_mfma_f32_16x16x32_bf16 v[116:119], v[164:167], v[180:183], v[116:119]
	v_mfma_f32_16x16x32_bf16 v[108:111], v[172:175], v[180:183], v[108:111]
	v_mfma_f32_16x16x32_bf16 v[100:103], v[164:167], v[196:199], v[100:103]
	v_mfma_f32_16x16x32_bf16 v[92:95], v[172:175], v[196:199], v[92:95]
	v_mfma_f32_16x16x32_bf16 v[84:87], v[164:167], v[204:207], v[84:87]
	v_mfma_f32_16x16x32_bf16 v[76:79], v[172:175], v[204:207], v[76:79]
	v_mfma_f32_16x16x32_bf16 v[68:71], v[164:167], v[212:215], v[68:71]
	v_mfma_f32_16x16x32_bf16 v[64:67], v[172:175], v[212:215], v[64:67]
	s_setprio 0
	s_barrier
	s_add_u32 s46, s24, 0x20000
	s_addc_u32 s47, s25, 0
	s_add_i32 s48, s48, s29
	v_lshl_add_u64 v[188:189], s[46:47], 0, v[128:129]
	s_mov_b32 m0, s48
	ds_read_b128 v[176:179], v195 offset:49152
	ds_read_b128 v[180:183], v195 offset:50176
	ds_read_b128 v[184:187], v195 offset:51200
	ds_read_b128 v[196:199], v195 offset:52224
	ds_read_b128 v[200:203], v195 offset:53248
	ds_read_b128 v[204:207], v195 offset:54272
	ds_read_b128 v[208:211], v195 offset:55296
	ds_read_b128 v[212:215], v195 offset:56320
	global_load_lds_dwordx4 v[188:189], off
	s_add_i32 m0, s48, 0x2000
	s_add_u32 s24, s24, 0x24000
	v_lshl_add_u64 v[188:189], s[46:47], 0, v[130:131]
	s_addc_u32 s25, s25, 0
	s_add_i32 s46, s49, s29
	global_load_lds_dwordx4 v[188:189], off
	v_lshl_add_u64 v[188:189], s[24:25], 0, v[128:129]
	s_mov_b32 m0, s46
	s_or_b32 s6, s6, 1
	global_load_lds_dwordx4 v[188:189], off
	v_lshl_add_u64 v[188:189], s[24:25], 0, v[130:131]
	s_add_i32 m0, s46, 0x2000
	s_lshl_b64 s[24:25], s[6:7], 21
	s_add_u32 s24, s27, s24
	s_addc_u32 s25, s26, s25
	global_load_lds_dwordx4 v[188:189], off
	v_lshl_add_u64 v[188:189], s[24:25], 0, v[128:129]
	s_mov_b32 m0, s36
	s_nop 0
	global_load_lds_dwordx4 v[188:189], off
	v_lshl_add_u64 v[188:189], s[24:25], 0, v[130:131]
	s_mov_b32 m0, s37
	s_nop 0
	global_load_lds_dwordx4 v[188:189], off
	s_waitcnt vmcnt(8)
	s_waitcnt lgkmcnt(0)
	s_barrier
	s_setprio 1
	v_mfma_f32_16x16x32_bf16 v[60:63], v[144:147], v[176:179], v[60:63]
	v_mfma_f32_16x16x32_bf16 v[56:59], v[152:155], v[176:179], v[56:59]
	v_mfma_f32_16x16x32_bf16 v[48:51], v[144:147], v[184:187], v[48:51]
	v_mfma_f32_16x16x32_bf16 v[40:43], v[152:155], v[184:187], v[40:43]
	v_mfma_f32_16x16x32_bf16 v[32:35], v[144:147], v[200:203], v[32:35]
	v_mfma_f32_16x16x32_bf16 v[24:27], v[152:155], v[200:203], v[24:27]
	v_mfma_f32_16x16x32_bf16 v[16:19], v[144:147], v[208:211], v[16:19]
	v_mfma_f32_16x16x32_bf16 v[8:11], v[152:155], v[208:211], v[8:11]
	v_mfma_f32_16x16x32_bf16 v[60:63], v[148:151], v[180:183], v[60:63]
	v_mfma_f32_16x16x32_bf16 v[56:59], v[156:159], v[180:183], v[56:59]
	v_mfma_f32_16x16x32_bf16 v[48:51], v[148:151], v[196:199], v[48:51]
	v_mfma_f32_16x16x32_bf16 v[40:43], v[156:159], v[196:199], v[40:43]
	v_mfma_f32_16x16x32_bf16 v[32:35], v[148:151], v[204:207], v[32:35]
	v_mfma_f32_16x16x32_bf16 v[24:27], v[156:159], v[204:207], v[24:27]
	v_mfma_f32_16x16x32_bf16 v[16:19], v[148:151], v[212:215], v[16:19]
	v_mfma_f32_16x16x32_bf16 v[8:11], v[156:159], v[212:215], v[8:11]
	v_mfma_f32_16x16x32_bf16 v[52:55], v[160:163], v[176:179], v[52:55]
	v_mfma_f32_16x16x32_bf16 v[44:47], v[168:171], v[176:179], v[44:47]
	v_mfma_f32_16x16x32_bf16 v[36:39], v[160:163], v[184:187], v[36:39]
	v_mfma_f32_16x16x32_bf16 v[28:31], v[168:171], v[184:187], v[28:31]
	v_mfma_f32_16x16x32_bf16 v[20:23], v[160:163], v[200:203], v[20:23]
	v_mfma_f32_16x16x32_bf16 v[12:15], v[168:171], v[200:203], v[12:15]
	v_mfma_f32_16x16x32_bf16 v[4:7], v[160:163], v[208:211], v[4:7]
	v_mfma_f32_16x16x32_bf16 v[0:3], v[168:171], v[208:211], v[0:3]
	v_mfma_f32_16x16x32_bf16 v[52:55], v[164:167], v[180:183], v[52:55]
	v_mfma_f32_16x16x32_bf16 v[44:47], v[172:175], v[180:183], v[44:47]
	v_mfma_f32_16x16x32_bf16 v[36:39], v[164:167], v[196:199], v[36:39]
	v_mfma_f32_16x16x32_bf16 v[28:31], v[172:175], v[196:199], v[28:31]
	v_mfma_f32_16x16x32_bf16 v[20:23], v[164:167], v[204:207], v[20:23]
	v_mfma_f32_16x16x32_bf16 v[12:15], v[172:175], v[204:207], v[12:15]
	v_mfma_f32_16x16x32_bf16 v[4:7], v[164:167], v[212:215], v[4:7]
	v_mfma_f32_16x16x32_bf16 v[0:3], v[172:175], v[212:215], v[0:3]
	s_setprio 0
	s_barrier
	s_add_u32 s22, s22, 0x400000
	s_addc_u32 s23, s23, 0
	s_add_u32 s42, s42, 0x40000
	s_addc_u32 s43, s43, 0
	s_cmp_gt_u32 s44, 61
	s_mov_b32 s44, s45
	s_cbranch_scc0 .LBB0_678
	v_lshl_or_b32 v142, s41, 8, v192
	v_lshl_add_u32 v144, s18, 8, v190
	v_ashrrev_i32_e32 v143, 31, v142
	v_ashrrev_i32_e32 v145, 31, v144
	v_lshl_add_u64 v[146:147], v[142:143], 1, s[12:13]
	v_lshlrev_b64 v[140:141], 11, v[144:145]
	v_lshl_add_u64 v[140:141], v[146:147], 0, v[140:141]
	global_load_dwordx2 v[196:197], v[140:141], off
	global_load_dwordx2 v[198:199], v[140:141], off offset:32
	global_load_dwordx2 v[200:201], v[140:141], off offset:256
	v_or_b32_e32 v202, 16, v144
	v_ashrrev_i32_e32 v203, 31, v202
	global_load_dwordx2 v[204:205], v[140:141], off offset:288
	v_lshlrev_b64 v[140:141], 11, v[202:203]
	v_lshl_add_u64 v[148:149], v[146:147], 0, v[140:141]
	global_load_dwordx2 v[206:207], v[148:149], off
	global_load_dwordx2 v[208:209], v[148:149], off offset:32
	global_load_dwordx2 v[210:211], v[148:149], off offset:256
	global_load_dwordx2 v[212:213], v[148:149], off offset:288
	v_or_b32_e32 v188, 32, v144
	v_or_b32_e32 v178, 48, v144
	v_add_u32_e32 v168, 0x80, v144
	v_add_u32_e32 v160, 0x90, v144
	v_add_u32_e32 v150, 0xa0, v144
	v_add_u32_e32 v140, 0xb0, v144
	v_ashrrev_i32_e32 v189, 31, v188
	v_ashrrev_i32_e32 v179, 31, v178
	v_ashrrev_i32_e32 v169, 31, v168
	v_ashrrev_i32_e32 v161, 31, v160
	v_ashrrev_i32_e32 v151, 31, v150
	v_ashrrev_i32_e32 v141, 31, v140
	v_lshlrev_b64 v[152:153], 12, v[144:145]
	v_lshlrev_b64 v[144:145], 2, v[142:143]
	v_lshlrev_b64 v[142:143], 11, v[188:189]
	v_lshlrev_b64 v[154:155], 11, v[178:179]
	v_lshlrev_b64 v[156:157], 11, v[168:169]
	v_lshlrev_b64 v[158:159], 11, v[160:161]
	v_lshlrev_b64 v[162:163], 11, v[150:151]
	v_lshlrev_b64 v[164:165], 11, v[140:141]
	v_lshl_add_u64 v[152:153], s[78:79], 0, v[152:153]
	v_lshl_add_u64 v[142:143], v[146:147], 0, v[142:143]
	v_lshl_add_u64 v[154:155], v[146:147], 0, v[154:155]
	v_lshl_add_u64 v[156:157], v[146:147], 0, v[156:157]
	v_lshl_add_u64 v[158:159], v[146:147], 0, v[158:159]
	v_lshl_add_u64 v[148:149], v[146:147], 0, v[162:163]
	v_lshl_add_u64 v[214:215], v[146:147], 0, v[164:165]
	v_lshl_add_u64 v[216:217], v[152:153], 0, v[144:145]
	global_load_dwordx2 v[218:219], v[142:143], off
	global_load_dwordx2 v[220:221], v[142:143], off offset:32
	global_load_dwordx2 v[222:223], v[142:143], off offset:256
	global_load_dwordx2 v[224:225], v[142:143], off offset:288
	global_load_dwordx2 v[226:227], v[154:155], off
	global_load_dwordx2 v[228:229], v[154:155], off offset:32
	global_load_dwordx2 v[186:187], v[154:155], off offset:256
	global_load_dwordx2 v[184:185], v[154:155], off offset:288
	global_load_dwordx2 v[182:183], v[156:157], off
	global_load_dwordx2 v[180:181], v[156:157], off offset:32
	global_load_dwordx2 v[176:177], v[156:157], off offset:256
	global_load_dwordx2 v[174:175], v[156:157], off offset:288
	global_load_dwordx2 v[172:173], v[158:159], off
	global_load_dwordx2 v[170:171], v[158:159], off offset:32
	global_load_dwordx2 v[166:167], v[158:159], off offset:256
	global_load_dwordx2 v[164:165], v[158:159], off offset:288
	global_load_dwordx2 v[162:163], v[148:149], off
	s_nop 0
	global_load_dwordx2 v[158:159], v[148:149], off offset:32
	global_load_dwordx2 v[156:157], v[148:149], off offset:256
	global_load_dwordx2 v[154:155], v[148:149], off offset:288
	global_load_dwordx2 v[152:153], v[214:215], off
	s_nop 0
	global_load_dwordx2 v[148:149], v[214:215], off offset:32
	global_load_dwordx2 v[146:147], v[214:215], off offset:256
	global_load_dwordx2 v[142:143], v[214:215], off offset:288
	s_and_b64 vcc, exec, s[0:1]
	s_mov_b32 s41, s8
	s_mov_b32 s18, s10
	s_mov_b64 s[22:23], s[16:17]
	s_mov_b64 s[20:21], s[14:15]
	s_waitcnt vmcnt(0)
	v_lshlrev_b32_e32 v214, 16, v196
	v_and_b32_e32 v215, 0xffff0000, v196
	v_lshlrev_b32_e32 v196, 16, v197
	v_and_b32_e32 v197, 0xffff0000, v197
	v_lshlrev_b32_e32 v230, 16, v198
	v_and_b32_e32 v231, 0xffff0000, v198
	v_lshlrev_b32_e32 v198, 16, v199
	v_and_b32_e32 v199, 0xffff0000, v199
	v_pk_add_f32 v[126:127], v[126:127], v[196:197]
	v_pk_add_f32 v[124:125], v[124:125], v[214:215]
	v_pk_add_f32 v[120:121], v[120:121], v[230:231]
	v_lshlrev_b32_e32 v232, 16, v200
	v_and_b32_e32 v233, 0xffff0000, v200
	v_pk_add_f32 v[122:123], v[122:123], v[198:199]
	global_store_dwordx4 v[216:217], v[124:127], off
	global_store_dwordx4 v[216:217], v[120:123], off offset:64
	v_pk_add_f32 v[116:117], v[116:117], v[232:233]
	s_nop 0
	v_lshlrev_b32_e32 v120, 16, v201
	v_and_b32_e32 v121, 0xffff0000, v201
	v_pk_add_f32 v[118:119], v[118:119], v[120:121]
	global_store_dwordx4 v[216:217], v[116:119], off offset:512
	s_nop 1
	v_lshlrev_b32_e32 v116, 16, v204
	v_and_b32_e32 v117, 0xffff0000, v204
	v_lshlrev_b32_e32 v118, 16, v205
	v_and_b32_e32 v119, 0xffff0000, v205
	v_pk_add_f32 v[110:111], v[110:111], v[118:119]
	v_pk_add_f32 v[108:109], v[108:109], v[116:117]
	global_store_dwordx4 v[216:217], v[108:111], off offset:576
	v_lshlrev_b64 v[116:117], 12, v[202:203]
	s_nop 0
	v_lshlrev_b32_e32 v108, 16, v206
	v_and_b32_e32 v109, 0xffff0000, v206
	v_lshlrev_b32_e32 v110, 16, v207
	v_and_b32_e32 v111, 0xffff0000, v207
	v_pk_add_f32 v[108:109], v[112:113], v[108:109]
	v_lshl_add_u64 v[112:113], s[78:79], 0, v[116:117]
	v_pk_add_f32 v[110:111], v[114:115], v[110:111]
	v_lshl_add_u64 v[112:113], v[112:113], 0, v[144:145]
	global_store_dwordx4 v[112:113], v[108:111], off
	s_nop 1
	v_lshlrev_b32_e32 v108, 16, v208
	v_and_b32_e32 v109, 0xffff0000, v208
	v_lshlrev_b32_e32 v110, 16, v209
	v_and_b32_e32 v111, 0xffff0000, v209
	v_pk_add_f32 v[106:107], v[106:107], v[110:111]
	v_pk_add_f32 v[104:105], v[104:105], v[108:109]
	global_store_dwordx4 v[112:113], v[104:107], off offset:64
	s_nop 1
	v_lshlrev_b32_e32 v104, 16, v210
	v_and_b32_e32 v105, 0xffff0000, v210
	v_lshlrev_b32_e32 v106, 16, v211
	v_and_b32_e32 v107, 0xffff0000, v211
	v_pk_add_f32 v[102:103], v[102:103], v[106:107]
	v_pk_add_f32 v[100:101], v[100:101], v[104:105]
	global_store_dwordx4 v[112:113], v[100:103], off offset:512
	s_nop 1
	v_lshlrev_b32_e32 v100, 16, v212
	v_and_b32_e32 v101, 0xffff0000, v212
	v_lshlrev_b32_e32 v102, 16, v213
	v_and_b32_e32 v103, 0xffff0000, v213
	v_pk_add_f32 v[94:95], v[94:95], v[102:103]
	v_pk_add_f32 v[92:93], v[92:93], v[100:101]
	global_store_dwordx4 v[112:113], v[92:95], off offset:576
	v_lshlrev_b64 v[100:101], 12, v[188:189]
	s_nop 0
	v_lshlrev_b32_e32 v92, 16, v218
	v_and_b32_e32 v93, 0xffff0000, v218
	v_lshlrev_b32_e32 v94, 16, v219
	v_and_b32_e32 v95, 0xffff0000, v219
	v_pk_add_f32 v[92:93], v[96:97], v[92:93]
	v_lshl_add_u64 v[96:97], s[78:79], 0, v[100:101]
	v_pk_add_f32 v[94:95], v[98:99], v[94:95]
	v_lshl_add_u64 v[96:97], v[96:97], 0, v[144:145]
	global_store_dwordx4 v[96:97], v[92:95], off
	s_nop 1
	v_lshlrev_b32_e32 v92, 16, v220
	v_and_b32_e32 v93, 0xffff0000, v220
	v_lshlrev_b32_e32 v94, 16, v221
	v_and_b32_e32 v95, 0xffff0000, v221
	v_pk_add_f32 v[90:91], v[90:91], v[94:95]
	v_pk_add_f32 v[88:89], v[88:89], v[92:93]
	global_store_dwordx4 v[96:97], v[88:91], off offset:64
	s_nop 1
	v_lshlrev_b32_e32 v88, 16, v222
	v_and_b32_e32 v89, 0xffff0000, v222
	v_lshlrev_b32_e32 v90, 16, v223
	v_and_b32_e32 v91, 0xffff0000, v223
	v_pk_add_f32 v[86:87], v[86:87], v[90:91]
	v_pk_add_f32 v[84:85], v[84:85], v[88:89]
	global_store_dwordx4 v[96:97], v[84:87], off offset:512
	s_nop 1
	v_lshlrev_b32_e32 v84, 16, v224
	v_and_b32_e32 v85, 0xffff0000, v224
	v_lshlrev_b32_e32 v86, 16, v225
	v_and_b32_e32 v87, 0xffff0000, v225
	v_pk_add_f32 v[78:79], v[78:79], v[86:87]
	v_pk_add_f32 v[76:77], v[76:77], v[84:85]
	global_store_dwordx4 v[96:97], v[76:79], off offset:576
	v_lshlrev_b64 v[84:85], 12, v[178:179]
	s_nop 0
	v_lshlrev_b32_e32 v76, 16, v226
	v_and_b32_e32 v77, 0xffff0000, v226
	v_lshlrev_b32_e32 v78, 16, v227
	v_and_b32_e32 v79, 0xffff0000, v227
	v_pk_add_f32 v[76:77], v[80:81], v[76:77]
	v_lshl_add_u64 v[80:81], s[78:79], 0, v[84:85]
	v_pk_add_f32 v[78:79], v[82:83], v[78:79]
	v_lshl_add_u64 v[80:81], v[80:81], 0, v[144:145]
	global_store_dwordx4 v[80:81], v[76:79], off
	s_nop 1
	v_lshlrev_b32_e32 v76, 16, v228
	v_and_b32_e32 v77, 0xffff0000, v228
	v_lshlrev_b32_e32 v78, 16, v229
	v_and_b32_e32 v79, 0xffff0000, v229
	v_pk_add_f32 v[74:75], v[74:75], v[78:79]
	v_pk_add_f32 v[72:73], v[72:73], v[76:77]
	global_store_dwordx4 v[80:81], v[72:75], off offset:64
	s_nop 1
	v_lshlrev_b32_e32 v72, 16, v186
	v_and_b32_e32 v73, 0xffff0000, v186
	v_lshlrev_b32_e32 v74, 16, v187
	v_and_b32_e32 v75, 0xffff0000, v187
	v_pk_add_f32 v[70:71], v[70:71], v[74:75]
	v_pk_add_f32 v[68:69], v[68:69], v[72:73]
	global_store_dwordx4 v[80:81], v[68:71], off offset:512
	s_nop 1
	v_lshlrev_b32_e32 v68, 16, v184
	v_and_b32_e32 v69, 0xffff0000, v184
	v_lshlrev_b32_e32 v70, 16, v185
	v_and_b32_e32 v71, 0xffff0000, v185
	v_pk_add_f32 v[66:67], v[66:67], v[70:71]
	v_pk_add_f32 v[64:65], v[64:65], v[68:69]
	global_store_dwordx4 v[80:81], v[64:67], off offset:576
	v_lshlrev_b32_e32 v68, 16, v183
	v_and_b32_e32 v69, 0xffff0000, v183
	v_lshlrev_b64 v[64:65], 12, v[168:169]
	v_lshlrev_b32_e32 v66, 16, v182
	v_and_b32_e32 v67, 0xffff0000, v182
	v_lshl_add_u64 v[64:65], s[78:79], 0, v[64:65]
	v_pk_add_f32 v[62:63], v[62:63], v[68:69]
	v_pk_add_f32 v[60:61], v[60:61], v[66:67]
	v_lshl_add_u64 v[64:65], v[64:65], 0, v[144:145]
	global_store_dwordx4 v[64:65], v[60:63], off
	s_nop 1
	v_lshlrev_b32_e32 v60, 16, v180
	v_and_b32_e32 v61, 0xffff0000, v180
	v_lshlrev_b32_e32 v62, 16, v181
	v_and_b32_e32 v63, 0xffff0000, v181
	v_pk_add_f32 v[58:59], v[58:59], v[62:63]
	v_pk_add_f32 v[56:57], v[56:57], v[60:61]
	global_store_dwordx4 v[64:65], v[56:59], off offset:64
	s_nop 1
	v_lshlrev_b32_e32 v56, 16, v176
	v_and_b32_e32 v57, 0xffff0000, v176
	v_lshlrev_b32_e32 v58, 16, v177
	v_and_b32_e32 v59, 0xffff0000, v177
	v_pk_add_f32 v[54:55], v[54:55], v[58:59]
	v_pk_add_f32 v[52:53], v[52:53], v[56:57]
	global_store_dwordx4 v[64:65], v[52:55], off offset:512
	s_nop 1
	v_lshlrev_b32_e32 v52, 16, v174
	v_and_b32_e32 v53, 0xffff0000, v174
	v_lshlrev_b32_e32 v54, 16, v175
	v_and_b32_e32 v55, 0xffff0000, v175
	v_pk_add_f32 v[46:47], v[46:47], v[54:55]
	v_pk_add_f32 v[44:45], v[44:45], v[52:53]
	global_store_dwordx4 v[64:65], v[44:47], off offset:576
	v_lshlrev_b64 v[52:53], 12, v[160:161]
	s_nop 0
	v_lshlrev_b32_e32 v44, 16, v172
	v_and_b32_e32 v45, 0xffff0000, v172
	v_lshlrev_b32_e32 v46, 16, v173
	v_and_b32_e32 v47, 0xffff0000, v173
	v_pk_add_f32 v[44:45], v[48:49], v[44:45]
	v_lshl_add_u64 v[48:49], s[78:79], 0, v[52:53]
	v_pk_add_f32 v[46:47], v[50:51], v[46:47]
	v_lshl_add_u64 v[48:49], v[48:49], 0, v[144:145]
	global_store_dwordx4 v[48:49], v[44:47], off
	s_nop 1
	v_lshlrev_b32_e32 v44, 16, v170
	v_and_b32_e32 v45, 0xffff0000, v170
	v_lshlrev_b32_e32 v46, 16, v171
	v_and_b32_e32 v47, 0xffff0000, v171
	v_pk_add_f32 v[42:43], v[42:43], v[46:47]
	v_pk_add_f32 v[40:41], v[40:41], v[44:45]
	global_store_dwordx4 v[48:49], v[40:43], off offset:64
	s_nop 1
	v_lshlrev_b32_e32 v40, 16, v166
	v_and_b32_e32 v41, 0xffff0000, v166
	v_lshlrev_b32_e32 v42, 16, v167
	v_and_b32_e32 v43, 0xffff0000, v167
	v_pk_add_f32 v[38:39], v[38:39], v[42:43]
	v_pk_add_f32 v[36:37], v[36:37], v[40:41]
	global_store_dwordx4 v[48:49], v[36:39], off offset:512
	s_nop 1
	v_lshlrev_b32_e32 v36, 16, v164
	v_and_b32_e32 v37, 0xffff0000, v164
	v_lshlrev_b32_e32 v38, 16, v165
	v_and_b32_e32 v39, 0xffff0000, v165
	v_pk_add_f32 v[30:31], v[30:31], v[38:39]
	v_pk_add_f32 v[28:29], v[28:29], v[36:37]
	global_store_dwordx4 v[48:49], v[28:31], off offset:576
	v_lshlrev_b64 v[36:37], 12, v[150:151]
	s_nop 0
	v_lshlrev_b32_e32 v28, 16, v162
	v_and_b32_e32 v29, 0xffff0000, v162
	v_lshlrev_b32_e32 v30, 16, v163
	v_and_b32_e32 v31, 0xffff0000, v163
	v_pk_add_f32 v[28:29], v[32:33], v[28:29]
	v_lshl_add_u64 v[32:33], s[78:79], 0, v[36:37]
	v_pk_add_f32 v[30:31], v[34:35], v[30:31]
	v_lshl_add_u64 v[32:33], v[32:33], 0, v[144:145]
	global_store_dwordx4 v[32:33], v[28:31], off
	s_nop 1
	v_lshlrev_b32_e32 v28, 16, v158
	v_and_b32_e32 v29, 0xffff0000, v158
	v_lshlrev_b32_e32 v30, 16, v159
	v_and_b32_e32 v31, 0xffff0000, v159
	v_pk_add_f32 v[26:27], v[26:27], v[30:31]
	v_pk_add_f32 v[24:25], v[24:25], v[28:29]
	global_store_dwordx4 v[32:33], v[24:27], off offset:64
	s_nop 1
	v_lshlrev_b32_e32 v24, 16, v156
	v_and_b32_e32 v25, 0xffff0000, v156
	v_lshlrev_b32_e32 v26, 16, v157
	v_and_b32_e32 v27, 0xffff0000, v157
	v_pk_add_f32 v[22:23], v[22:23], v[26:27]
	v_pk_add_f32 v[20:21], v[20:21], v[24:25]
	global_store_dwordx4 v[32:33], v[20:23], off offset:512
	s_nop 1
	v_lshlrev_b32_e32 v20, 16, v154
	v_and_b32_e32 v21, 0xffff0000, v154
	v_lshlrev_b32_e32 v22, 16, v155
	v_and_b32_e32 v23, 0xffff0000, v155
	v_pk_add_f32 v[14:15], v[14:15], v[22:23]
	v_pk_add_f32 v[12:13], v[12:13], v[20:21]
	global_store_dwordx4 v[32:33], v[12:15], off offset:576
	v_lshlrev_b64 v[20:21], 12, v[140:141]
	s_nop 0
	v_lshlrev_b32_e32 v12, 16, v152
	v_and_b32_e32 v13, 0xffff0000, v152
	v_lshlrev_b32_e32 v14, 16, v153
	v_and_b32_e32 v15, 0xffff0000, v153
	v_pk_add_f32 v[12:13], v[16:17], v[12:13]
	v_lshl_add_u64 v[16:17], s[78:79], 0, v[20:21]
	v_pk_add_f32 v[14:15], v[18:19], v[14:15]
	v_lshl_add_u64 v[16:17], v[16:17], 0, v[144:145]
	global_store_dwordx4 v[16:17], v[12:15], off
	s_nop 1
	v_lshlrev_b32_e32 v12, 16, v148
	v_and_b32_e32 v13, 0xffff0000, v148
	v_lshlrev_b32_e32 v14, 16, v149
	v_and_b32_e32 v15, 0xffff0000, v149
	v_pk_add_f32 v[10:11], v[10:11], v[14:15]
	v_pk_add_f32 v[8:9], v[8:9], v[12:13]
	global_store_dwordx4 v[16:17], v[8:11], off offset:64
	s_nop 1
	v_lshlrev_b32_e32 v8, 16, v146
	v_and_b32_e32 v9, 0xffff0000, v146
	v_lshlrev_b32_e32 v10, 16, v147
	v_and_b32_e32 v11, 0xffff0000, v147
	v_pk_add_f32 v[6:7], v[6:7], v[10:11]
	v_pk_add_f32 v[4:5], v[4:5], v[8:9]
	global_store_dwordx4 v[16:17], v[4:7], off offset:512
	s_nop 1
	v_lshlrev_b32_e32 v4, 16, v142
	v_and_b32_e32 v5, 0xffff0000, v142
	v_lshlrev_b32_e32 v6, 16, v143
	v_and_b32_e32 v7, 0xffff0000, v143
	v_pk_add_f32 v[2:3], v[2:3], v[6:7]
	v_pk_add_f32 v[0:1], v[0:1], v[4:5]
	global_store_dwordx4 v[16:17], v[0:3], off offset:576
	s_cbranch_vccz .LBB0_671
	s_waitcnt vmcnt(0)
	s_cmpk_gt_u32 s28, 0xff
	s_cbranch_scc1 .LBB0_682
	s_barrier
